# LRU pass2 packed f32 + alpha loop sub-iterations interleaved + epilogue lane exchange via v_cndmask dpp
# speedup vs baseline: 1.0129x; 1.0129x over previous
; #define LAS __attribute__((address_space(3)))
; __device__ __forceinline__ unsigned cvt_pk_bf16(float lo, float hi) { unsigned r; asm volatile("v_cvt_pk_bf16_f32 %0, %1, %2" : "=v"(r) : "v"(lo), "v"(hi)); return r; }
; __device__ __forceinline__ float rinv_from(u64 v) { return rsqrtf((float)v * (1.0f / 16777216.0f) * (1.0f / 1024.0f) + RMS_EPS); }
;     __device__ __forceinline__ void operator()(const f32x4 (&acc)[2][2][4][2], const Unit& u, int wr, int wc, int fr, int fq) const {
;         const int ln = fr + 16 * fq; const int colw = u.pn * BM + 64 * wc;
;         if (colw >= nvalid) return;
;         float rl[2];
; #pragma unroll
;         for (int ai = 0; ai < 2; ++ai) rl[ai] = rinv_from(ssq[u.pm * BM + ai * HALF + wr * 64 + ln]);
;         LAS unsigned char* sl = stg + (wr * 4 + wc) * EPI_STG_SLICE;
;         const int rr = ln >> 3, cc = ln & 7;
; #pragma unroll
;         for (int ai = 0; ai < 2; ++ai)
; #pragma unroll
;             for (int m = 0; m < 4; ++m) {
;                 const float sc = __shfl(rl[ai], 16 * m + fr);
; #pragma unroll
;                 for (int bj = 0; bj < 2; ++bj) {
;                     f32x4 v0 = acc[ai][bj][m][0] * sc, v1 = acc[ai][bj][m][1] * sc;
;                     if (ACT == 1) {
; #pragma unroll
;                         for (int e = 0; e < 4; ++e) { float a = fmaxf(v0[e], 0.f), b = fmaxf(v1[e], 0.f); v0[e] = a * a; v1[e] = b * b; }
;                     }
;                     u32x4 w; w.x = cvt_pk_bf16(v0[0], v0[1]); w.y = cvt_pk_bf16(v0[2], v0[3]); w.z = cvt_pk_bf16(v1[0], v1[1]); w.w = cvt_pk_bf16(v1[2], v1[3]);
;                     *(LAS u32x4*)(sl + fr * 144 + bj * 64 + fq * 16) = w;
;                 }
;                 const int rowb = u.pm * BM + ai * HALF + wr * 64 + m * 16;
; #pragma unroll
;                 for (int i = 0; i < 2; ++i) { const int r = rr + 8 * i; const u32x4 q = *(const LAS u32x4*)(sl + r * 144 + cc * 16);
;                     __builtin_nontemporal_store(q, (u32x4*)(O + (size_t)(rowb + r) * ldc + colw + cc * 8)); }
.LBB0_114:
	s_lshl_b32 s3, s2, 8
	v_add_u32_e32 v162, s3, v155
	v_ashrrev_i32_e32 v163, 31, v162
	v_lshl_add_u64 v[162:163], v[162:163], 3, s[42:43]
	v_mov_b32_e32 v164, v156
	v_mov_b32_e32 v165, v157
	s_nop 0
	v_mov_b32_e32 v162, v159
	s_mov_b32 s2, 0x33800000
	s_ashr_i32 s27, s26, 31
	s_add_i32 s6, s3, s81
	v_mov_b32_e32 v163, v160
	v_ffbh_u32_e32 v153, v165
	v_min_u32_e32 v153, 32, v153
	v_lshlrev_b64 v[164:165], v153, v[164:165]
	v_min_u32_e32 v161, 1, v164
	v_or_b32_e32 v161, v165, v161
	v_cvt_f32_u32_e32 v161, v161
	v_sub_u32_e32 v153, 32, v153
	v_ldexp_f32 v165, v161, v153
	v_ffbh_u32_e32 v153, v163
	v_min_u32_e32 v153, 32, v153
	v_lshlrev_b64 v[162:163], v153, v[162:163]
	v_min_u32_e32 v161, 1, v162
	v_or_b32_e32 v161, v163, v161
	v_cvt_f32_u32_e32 v161, v161
	v_sub_u32_e32 v153, 32, v153
	v_ldexp_f32 v164, v161, v153
	v_pk_mul_f32 v[162:163], v[164:165], s[2:3] op_sel_hi:[1,0]
	s_mov_b32 s2, 0x3a800000
	v_pk_fma_f32 v[162:163], v[162:163], s[2:3], v[138:139] op_sel_hi:[1,0,0]
	s_add_i32 s2, s3, s77
	v_mul_f32_e32 v153, 0x4b800000, v163
	v_cmp_gt_f32_e64 s[38:39], s70, v163
	v_cmp_gt_f32_e32 vcc, s70, v162
	s_nop 0
	v_cndmask_b32_e64 v153, v163, v153, s[38:39]
	v_rsq_f32_e32 v153, v153
	s_nop 0
	v_mul_f32_e32 v161, 0x45800000, v153
	v_cndmask_b32_e64 v163, v153, v161, s[38:39]
	v_mul_f32_e32 v153, 0x4b800000, v162
	v_cndmask_b32_e32 v153, v162, v153, vcc
	v_rsq_f32_e32 v153, v153
	s_lshl_b64 s[38:39], s[26:27], 1
	v_mul_f32_e32 v161, 0x45800000, v153
	v_cndmask_b32_e32 v161, v153, v161, vcc
	v_and_or_b32 v153, v177, 64, v1
	v_lshlrev_b32_e32 v162, 2, v153
	ds_bpermute_b32 v192, v162, v163
	ds_bpermute_b32 v194, v162, v163 offset:64
	ds_bpermute_b32 v196, v162, v163 offset:128
	ds_bpermute_b32 v198, v162, v163 offset:192
	ds_bpermute_b32 v200, v162, v161
	ds_bpermute_b32 v202, v162, v161 offset:64
	ds_bpermute_b32 v204, v162, v161 offset:128
	ds_bpermute_b32 v206, v162, v161 offset:192
	v_and_b32_e32 v210, 1, v177
	v_and_b32_e32 v211, 14, v177
	v_cmp_eq_u32_e64 s[92:93], 0, v210
	v_cmp_ne_u32_e64 s[98:99], 0, v210
	v_mul_u32_u24_e32 v208, 0x1300, v211
	s_mul_i32 s7, s2, 0x1300
	v_lshl_add_u32 v208, v210, 6, v208
	v_bfe_u32 v211, v177, 4, 2
	v_lshl_add_u32 v208, v211, 4, v208
	v_add_u32_e32 v209, 0x1300, v208
	s_add_u32 s62, s40, s7
	s_addc_u32 s63, s41, 0
	s_lshl_b32 s7, s26, 1
	s_add_u32 s62, s62, s7
	s_addc_u32 s63, s63, 0
	s_waitcnt lgkmcnt(7)
	s_mov_b32 s64, s62
	s_mov_b32 s65, s63
	v_pk_mul_f32 v[126:127], v[126:127], v[192:193] op_sel_hi:[1,0]
	v_pk_mul_f32 v[128:129], v[128:129], v[192:193] op_sel_hi:[1,0]
	v_pk_mul_f32 v[122:123], v[122:123], v[192:193] op_sel_hi:[1,0]
	v_pk_mul_f32 v[124:125], v[124:125], v[192:193] op_sel_hi:[1,0]
	v_cvt_pk_bf16_f32 v126, v126, v127
	v_cvt_pk_bf16_f32 v127, v128, v129
	v_cvt_pk_bf16_f32 v128, v122, v123
	v_cvt_pk_bf16_f32 v129, v124, v125
	v_pk_mul_f32 v[118:119], v[118:119], v[192:193] op_sel_hi:[1,0]
	v_pk_mul_f32 v[120:121], v[120:121], v[192:193] op_sel_hi:[1,0]
	v_pk_mul_f32 v[114:115], v[114:115], v[192:193] op_sel_hi:[1,0]
	v_pk_mul_f32 v[116:117], v[116:117], v[192:193] op_sel_hi:[1,0]
	v_cvt_pk_bf16_f32 v118, v118, v119
	v_cvt_pk_bf16_f32 v119, v120, v121
	v_cvt_pk_bf16_f32 v120, v114, v115
	v_cvt_pk_bf16_f32 v121, v116, v117
	s_mov_b64 vcc, s[98:99]
	v_cndmask_b32_dpp v122, v126, v118, vcc quad_perm:[1,0,3,2] row_mask:0xf bank_mask:0xf
	v_cndmask_b32_dpp v123, v127, v119, vcc quad_perm:[1,0,3,2] row_mask:0xf bank_mask:0xf
	v_cndmask_b32_dpp v124, v128, v120, vcc quad_perm:[1,0,3,2] row_mask:0xf bank_mask:0xf
	v_cndmask_b32_dpp v125, v129, v121, vcc quad_perm:[1,0,3,2] row_mask:0xf bank_mask:0xf
	s_mov_b64 vcc, s[92:93]
	v_cndmask_b32_dpp v126, v118, v126, vcc quad_perm:[1,0,3,2] row_mask:0xf bank_mask:0xf
	v_cndmask_b32_dpp v127, v119, v127, vcc quad_perm:[1,0,3,2] row_mask:0xf bank_mask:0xf
	v_cndmask_b32_dpp v128, v120, v128, vcc quad_perm:[1,0,3,2] row_mask:0xf bank_mask:0xf
	v_cndmask_b32_dpp v129, v121, v129, vcc quad_perm:[1,0,3,2] row_mask:0xf bank_mask:0xf
	global_store_dwordx4 v208, v[126:129], s[64:65] nt
	global_store_dwordx4 v209, v[122:125], s[64:65] nt
	s_waitcnt lgkmcnt(6)
	s_add_u32 s64, s62, 0x13000
	s_addc_u32 s65, s63, 0
	v_pk_mul_f32 v[110:111], v[110:111], v[194:195] op_sel_hi:[1,0]
	v_pk_mul_f32 v[112:113], v[112:113], v[194:195] op_sel_hi:[1,0]
	v_pk_mul_f32 v[106:107], v[106:107], v[194:195] op_sel_hi:[1,0]
	v_pk_mul_f32 v[108:109], v[108:109], v[194:195] op_sel_hi:[1,0]
	v_cvt_pk_bf16_f32 v110, v110, v111
	v_cvt_pk_bf16_f32 v111, v112, v113
	v_cvt_pk_bf16_f32 v112, v106, v107
	v_cvt_pk_bf16_f32 v113, v108, v109
	v_pk_mul_f32 v[102:103], v[102:103], v[194:195] op_sel_hi:[1,0]
	v_pk_mul_f32 v[104:105], v[104:105], v[194:195] op_sel_hi:[1,0]
	v_pk_mul_f32 v[98:99], v[98:99], v[194:195] op_sel_hi:[1,0]
	v_pk_mul_f32 v[100:101], v[100:101], v[194:195] op_sel_hi:[1,0]
	v_cvt_pk_bf16_f32 v102, v102, v103
	v_cvt_pk_bf16_f32 v103, v104, v105
	v_cvt_pk_bf16_f32 v104, v98, v99
	v_cvt_pk_bf16_f32 v105, v100, v101
	s_mov_b64 vcc, s[98:99]
	v_cndmask_b32_dpp v106, v110, v102, vcc quad_perm:[1,0,3,2] row_mask:0xf bank_mask:0xf
	v_cndmask_b32_dpp v107, v111, v103, vcc quad_perm:[1,0,3,2] row_mask:0xf bank_mask:0xf
	v_cndmask_b32_dpp v108, v112, v104, vcc quad_perm:[1,0,3,2] row_mask:0xf bank_mask:0xf
	v_cndmask_b32_dpp v109, v113, v105, vcc quad_perm:[1,0,3,2] row_mask:0xf bank_mask:0xf
	s_mov_b64 vcc, s[92:93]
	v_cndmask_b32_dpp v110, v102, v110, vcc quad_perm:[1,0,3,2] row_mask:0xf bank_mask:0xf
	v_cndmask_b32_dpp v111, v103, v111, vcc quad_perm:[1,0,3,2] row_mask:0xf bank_mask:0xf
	v_cndmask_b32_dpp v112, v104, v112, vcc quad_perm:[1,0,3,2] row_mask:0xf bank_mask:0xf
	v_cndmask_b32_dpp v113, v105, v113, vcc quad_perm:[1,0,3,2] row_mask:0xf bank_mask:0xf
	global_store_dwordx4 v208, v[110:113], s[64:65] nt
	global_store_dwordx4 v209, v[106:109], s[64:65] nt
	s_waitcnt lgkmcnt(5)
; #define LAS __attribute__((address_space(3)))
; __device__ __forceinline__ unsigned cvt_pk_bf16(float lo, float hi) { unsigned r; asm volatile("v_cvt_pk_bf16_f32 %0, %1, %2" : "=v"(r) : "v"(lo), "v"(hi)); return r; }
;     __device__ __forceinline__ void operator()(const f32x4 (&acc)[2][2][4][2], const Unit& u, int wr, int wc, int fr, int fq) const {
;     ...
;         for (int ai = 0; ai < 2; ++ai)
; #pragma unroll
;             for (int m = 0; m < 4; ++m) {
;                 const float sc = __shfl(rl[ai], 16 * m + fr);
; #pragma unroll
;                 for (int bj = 0; bj < 2; ++bj) {
;                     f32x4 v0 = acc[ai][bj][m][0] * sc, v1 = acc[ai][bj][m][1] * sc;
;                     if (ACT == 1) {
; #pragma unroll
;                         for (int e = 0; e < 4; ++e) { float a = fmaxf(v0[e], 0.f), b = fmaxf(v1[e], 0.f); v0[e] = a * a; v1[e] = b * b; }
;                     }
;                     u32x4 w; w.x = cvt_pk_bf16(v0[0], v0[1]); w.y = cvt_pk_bf16(v0[2], v0[3]); w.z = cvt_pk_bf16(v1[0], v1[1]); w.w = cvt_pk_bf16(v1[2], v1[3]);
;                     *(LAS u32x4*)(sl + fr * 144 + bj * 64 + fq * 16) = w;
;                 }
;                 const int rowb = u.pm * BM + ai * HALF + wr * 64 + m * 16;
; #pragma unroll
;                 for (int i = 0; i < 2; ++i) { const int r = rr + 8 * i; const u32x4 q = *(const LAS u32x4*)(sl + r * 144 + cc * 16);
;                     __builtin_nontemporal_store(q, (u32x4*)(O + (size_t)(rowb + r) * ldc + colw + cc * 8)); }
	s_add_u32 s64, s62, 0x26000
	s_addc_u32 s65, s63, 0
	v_pk_mul_f32 v[94:95], v[94:95], v[196:197] op_sel_hi:[1,0]
	v_pk_mul_f32 v[96:97], v[96:97], v[196:197] op_sel_hi:[1,0]
	v_pk_mul_f32 v[90:91], v[90:91], v[196:197] op_sel_hi:[1,0]
	v_pk_mul_f32 v[92:93], v[92:93], v[196:197] op_sel_hi:[1,0]
	v_cvt_pk_bf16_f32 v94, v94, v95
	v_cvt_pk_bf16_f32 v95, v96, v97
	v_cvt_pk_bf16_f32 v96, v90, v91
	v_cvt_pk_bf16_f32 v97, v92, v93
	v_pk_mul_f32 v[86:87], v[86:87], v[196:197] op_sel_hi:[1,0]
	v_pk_mul_f32 v[88:89], v[88:89], v[196:197] op_sel_hi:[1,0]
	v_pk_mul_f32 v[82:83], v[82:83], v[196:197] op_sel_hi:[1,0]
	v_pk_mul_f32 v[84:85], v[84:85], v[196:197] op_sel_hi:[1,0]
	v_cvt_pk_bf16_f32 v86, v86, v87
	v_cvt_pk_bf16_f32 v87, v88, v89
	v_cvt_pk_bf16_f32 v88, v82, v83
	v_cvt_pk_bf16_f32 v89, v84, v85
	s_mov_b64 vcc, s[98:99]
	v_cndmask_b32_dpp v90, v94, v86, vcc quad_perm:[1,0,3,2] row_mask:0xf bank_mask:0xf
	v_cndmask_b32_dpp v91, v95, v87, vcc quad_perm:[1,0,3,2] row_mask:0xf bank_mask:0xf
	v_cndmask_b32_dpp v92, v96, v88, vcc quad_perm:[1,0,3,2] row_mask:0xf bank_mask:0xf
	v_cndmask_b32_dpp v93, v97, v89, vcc quad_perm:[1,0,3,2] row_mask:0xf bank_mask:0xf
	s_mov_b64 vcc, s[92:93]
	v_cndmask_b32_dpp v94, v86, v94, vcc quad_perm:[1,0,3,2] row_mask:0xf bank_mask:0xf
	v_cndmask_b32_dpp v95, v87, v95, vcc quad_perm:[1,0,3,2] row_mask:0xf bank_mask:0xf
	v_cndmask_b32_dpp v96, v88, v96, vcc quad_perm:[1,0,3,2] row_mask:0xf bank_mask:0xf
	v_cndmask_b32_dpp v97, v89, v97, vcc quad_perm:[1,0,3,2] row_mask:0xf bank_mask:0xf
	global_store_dwordx4 v208, v[94:97], s[64:65] nt
	global_store_dwordx4 v209, v[90:93], s[64:65] nt
	s_waitcnt lgkmcnt(4)
	s_add_u32 s64, s62, 0x39000
	s_addc_u32 s65, s63, 0
	v_pk_mul_f32 v[78:79], v[78:79], v[198:199] op_sel_hi:[1,0]
	v_pk_mul_f32 v[80:81], v[80:81], v[198:199] op_sel_hi:[1,0]
	v_pk_mul_f32 v[74:75], v[74:75], v[198:199] op_sel_hi:[1,0]
	v_pk_mul_f32 v[76:77], v[76:77], v[198:199] op_sel_hi:[1,0]
	v_cvt_pk_bf16_f32 v78, v78, v79
	v_cvt_pk_bf16_f32 v79, v80, v81
	v_cvt_pk_bf16_f32 v80, v74, v75
	v_cvt_pk_bf16_f32 v81, v76, v77
	v_pk_mul_f32 v[70:71], v[70:71], v[198:199] op_sel_hi:[1,0]
	v_pk_mul_f32 v[72:73], v[72:73], v[198:199] op_sel_hi:[1,0]
	v_pk_mul_f32 v[66:67], v[66:67], v[198:199] op_sel_hi:[1,0]
	v_pk_mul_f32 v[68:69], v[68:69], v[198:199] op_sel_hi:[1,0]
	v_cvt_pk_bf16_f32 v70, v70, v71
	v_cvt_pk_bf16_f32 v71, v72, v73
	v_cvt_pk_bf16_f32 v72, v66, v67
	v_cvt_pk_bf16_f32 v73, v68, v69
	s_mov_b64 vcc, s[98:99]
	v_cndmask_b32_dpp v74, v78, v70, vcc quad_perm:[1,0,3,2] row_mask:0xf bank_mask:0xf
	v_cndmask_b32_dpp v75, v79, v71, vcc quad_perm:[1,0,3,2] row_mask:0xf bank_mask:0xf
	v_cndmask_b32_dpp v76, v80, v72, vcc quad_perm:[1,0,3,2] row_mask:0xf bank_mask:0xf
	v_cndmask_b32_dpp v77, v81, v73, vcc quad_perm:[1,0,3,2] row_mask:0xf bank_mask:0xf
	s_mov_b64 vcc, s[92:93]
	v_cndmask_b32_dpp v78, v70, v78, vcc quad_perm:[1,0,3,2] row_mask:0xf bank_mask:0xf
	v_cndmask_b32_dpp v79, v71, v79, vcc quad_perm:[1,0,3,2] row_mask:0xf bank_mask:0xf
	v_cndmask_b32_dpp v80, v72, v80, vcc quad_perm:[1,0,3,2] row_mask:0xf bank_mask:0xf
	v_cndmask_b32_dpp v81, v73, v81, vcc quad_perm:[1,0,3,2] row_mask:0xf bank_mask:0xf
	global_store_dwordx4 v208, v[78:81], s[64:65] nt
	global_store_dwordx4 v209, v[74:77], s[64:65] nt
	s_waitcnt lgkmcnt(3)
	s_add_u32 s64, s62, 0x98000
	s_addc_u32 s65, s63, 0
	v_pk_mul_f32 v[62:63], v[62:63], v[200:201] op_sel_hi:[1,0]
	v_pk_mul_f32 v[64:65], v[64:65], v[200:201] op_sel_hi:[1,0]
	v_pk_mul_f32 v[58:59], v[58:59], v[200:201] op_sel_hi:[1,0]
	v_pk_mul_f32 v[60:61], v[60:61], v[200:201] op_sel_hi:[1,0]
	v_cvt_pk_bf16_f32 v62, v62, v63
	v_cvt_pk_bf16_f32 v63, v64, v65
	v_cvt_pk_bf16_f32 v64, v58, v59
	v_cvt_pk_bf16_f32 v65, v60, v61
	v_pk_mul_f32 v[54:55], v[54:55], v[200:201] op_sel_hi:[1,0]
	v_pk_mul_f32 v[56:57], v[56:57], v[200:201] op_sel_hi:[1,0]
	v_pk_mul_f32 v[50:51], v[50:51], v[200:201] op_sel_hi:[1,0]
	v_pk_mul_f32 v[52:53], v[52:53], v[200:201] op_sel_hi:[1,0]
	v_cvt_pk_bf16_f32 v54, v54, v55
	v_cvt_pk_bf16_f32 v55, v56, v57
	v_cvt_pk_bf16_f32 v56, v50, v51
	v_cvt_pk_bf16_f32 v57, v52, v53
	s_mov_b64 vcc, s[98:99]
	v_cndmask_b32_dpp v58, v62, v54, vcc quad_perm:[1,0,3,2] row_mask:0xf bank_mask:0xf
	v_cndmask_b32_dpp v59, v63, v55, vcc quad_perm:[1,0,3,2] row_mask:0xf bank_mask:0xf
	v_cndmask_b32_dpp v60, v64, v56, vcc quad_perm:[1,0,3,2] row_mask:0xf bank_mask:0xf
	v_cndmask_b32_dpp v61, v65, v57, vcc quad_perm:[1,0,3,2] row_mask:0xf bank_mask:0xf
	s_mov_b64 vcc, s[92:93]
	v_cndmask_b32_dpp v62, v54, v62, vcc quad_perm:[1,0,3,2] row_mask:0xf bank_mask:0xf
	v_cndmask_b32_dpp v63, v55, v63, vcc quad_perm:[1,0,3,2] row_mask:0xf bank_mask:0xf
	v_cndmask_b32_dpp v64, v56, v64, vcc quad_perm:[1,0,3,2] row_mask:0xf bank_mask:0xf
	v_cndmask_b32_dpp v65, v57, v65, vcc quad_perm:[1,0,3,2] row_mask:0xf bank_mask:0xf
	global_store_dwordx4 v208, v[62:65], s[64:65] nt
	global_store_dwordx4 v209, v[58:61], s[64:65] nt
	s_waitcnt lgkmcnt(2)
; #define LAS __attribute__((address_space(3)))
; __device__ __forceinline__ unsigned cvt_pk_bf16(float lo, float hi) { unsigned r; asm volatile("v_cvt_pk_bf16_f32 %0, %1, %2" : "=v"(r) : "v"(lo), "v"(hi)); return r; }
;     __device__ __forceinline__ void operator()(const f32x4 (&acc)[2][2][4][2], const Unit& u, int wr, int wc, int fr, int fq) const {
;     ...
;         for (int ai = 0; ai < 2; ++ai)
; #pragma unroll
;             for (int m = 0; m < 4; ++m) {
;                 const float sc = __shfl(rl[ai], 16 * m + fr);
; #pragma unroll
;                 for (int bj = 0; bj < 2; ++bj) {
;                     f32x4 v0 = acc[ai][bj][m][0] * sc, v1 = acc[ai][bj][m][1] * sc;
;                     if (ACT == 1) {
; #pragma unroll
;                         for (int e = 0; e < 4; ++e) { float a = fmaxf(v0[e], 0.f), b = fmaxf(v1[e], 0.f); v0[e] = a * a; v1[e] = b * b; }
;                     }
;                     u32x4 w; w.x = cvt_pk_bf16(v0[0], v0[1]); w.y = cvt_pk_bf16(v0[2], v0[3]); w.z = cvt_pk_bf16(v1[0], v1[1]); w.w = cvt_pk_bf16(v1[2], v1[3]);
;                     *(LAS u32x4*)(sl + fr * 144 + bj * 64 + fq * 16) = w;
;                 }
;                 const int rowb = u.pm * BM + ai * HALF + wr * 64 + m * 16;
; #pragma unroll
;                 for (int i = 0; i < 2; ++i) { const int r = rr + 8 * i; const u32x4 q = *(const LAS u32x4*)(sl + r * 144 + cc * 16);
;                     __builtin_nontemporal_store(q, (u32x4*)(O + (size_t)(rowb + r) * ldc + colw + cc * 8)); }
	s_add_u32 s64, s62, 0xab000
	s_addc_u32 s65, s63, 0
	v_pk_mul_f32 v[46:47], v[46:47], v[202:203] op_sel_hi:[1,0]
	v_pk_mul_f32 v[48:49], v[48:49], v[202:203] op_sel_hi:[1,0]
	v_pk_mul_f32 v[42:43], v[42:43], v[202:203] op_sel_hi:[1,0]
	v_pk_mul_f32 v[44:45], v[44:45], v[202:203] op_sel_hi:[1,0]
	v_cvt_pk_bf16_f32 v46, v46, v47
	v_cvt_pk_bf16_f32 v47, v48, v49
	v_cvt_pk_bf16_f32 v48, v42, v43
	v_cvt_pk_bf16_f32 v49, v44, v45
	v_pk_mul_f32 v[38:39], v[38:39], v[202:203] op_sel_hi:[1,0]
	v_pk_mul_f32 v[40:41], v[40:41], v[202:203] op_sel_hi:[1,0]
	v_pk_mul_f32 v[34:35], v[34:35], v[202:203] op_sel_hi:[1,0]
	v_pk_mul_f32 v[36:37], v[36:37], v[202:203] op_sel_hi:[1,0]
	v_cvt_pk_bf16_f32 v38, v38, v39
	v_cvt_pk_bf16_f32 v39, v40, v41
	v_cvt_pk_bf16_f32 v40, v34, v35
	v_cvt_pk_bf16_f32 v41, v36, v37
	s_mov_b64 vcc, s[98:99]
	v_cndmask_b32_dpp v42, v46, v38, vcc quad_perm:[1,0,3,2] row_mask:0xf bank_mask:0xf
	v_cndmask_b32_dpp v43, v47, v39, vcc quad_perm:[1,0,3,2] row_mask:0xf bank_mask:0xf
	v_cndmask_b32_dpp v44, v48, v40, vcc quad_perm:[1,0,3,2] row_mask:0xf bank_mask:0xf
	v_cndmask_b32_dpp v45, v49, v41, vcc quad_perm:[1,0,3,2] row_mask:0xf bank_mask:0xf
	s_mov_b64 vcc, s[92:93]
	v_cndmask_b32_dpp v46, v38, v46, vcc quad_perm:[1,0,3,2] row_mask:0xf bank_mask:0xf
	v_cndmask_b32_dpp v47, v39, v47, vcc quad_perm:[1,0,3,2] row_mask:0xf bank_mask:0xf
	v_cndmask_b32_dpp v48, v40, v48, vcc quad_perm:[1,0,3,2] row_mask:0xf bank_mask:0xf
	v_cndmask_b32_dpp v49, v41, v49, vcc quad_perm:[1,0,3,2] row_mask:0xf bank_mask:0xf
	global_store_dwordx4 v208, v[46:49], s[64:65] nt
	global_store_dwordx4 v209, v[42:45], s[64:65] nt
	s_waitcnt lgkmcnt(1)
	s_add_u32 s64, s62, 0xbe000
	s_addc_u32 s65, s63, 0
	v_pk_mul_f32 v[30:31], v[30:31], v[204:205] op_sel_hi:[1,0]
	v_pk_mul_f32 v[32:33], v[32:33], v[204:205] op_sel_hi:[1,0]
	v_pk_mul_f32 v[26:27], v[26:27], v[204:205] op_sel_hi:[1,0]
	v_pk_mul_f32 v[28:29], v[28:29], v[204:205] op_sel_hi:[1,0]
	v_cvt_pk_bf16_f32 v30, v30, v31
	v_cvt_pk_bf16_f32 v31, v32, v33
	v_cvt_pk_bf16_f32 v32, v26, v27
	v_cvt_pk_bf16_f32 v33, v28, v29
	v_pk_mul_f32 v[22:23], v[22:23], v[204:205] op_sel_hi:[1,0]
	v_pk_mul_f32 v[24:25], v[24:25], v[204:205] op_sel_hi:[1,0]
	v_pk_mul_f32 v[18:19], v[18:19], v[204:205] op_sel_hi:[1,0]
	v_pk_mul_f32 v[20:21], v[20:21], v[204:205] op_sel_hi:[1,0]
	v_cvt_pk_bf16_f32 v22, v22, v23
	v_cvt_pk_bf16_f32 v23, v24, v25
	v_cvt_pk_bf16_f32 v24, v18, v19
	v_cvt_pk_bf16_f32 v25, v20, v21
	s_mov_b64 vcc, s[98:99]
	v_cndmask_b32_dpp v26, v30, v22, vcc quad_perm:[1,0,3,2] row_mask:0xf bank_mask:0xf
	v_cndmask_b32_dpp v27, v31, v23, vcc quad_perm:[1,0,3,2] row_mask:0xf bank_mask:0xf
	v_cndmask_b32_dpp v28, v32, v24, vcc quad_perm:[1,0,3,2] row_mask:0xf bank_mask:0xf
	v_cndmask_b32_dpp v29, v33, v25, vcc quad_perm:[1,0,3,2] row_mask:0xf bank_mask:0xf
	s_mov_b64 vcc, s[92:93]
	v_cndmask_b32_dpp v30, v22, v30, vcc quad_perm:[1,0,3,2] row_mask:0xf bank_mask:0xf
	v_cndmask_b32_dpp v31, v23, v31, vcc quad_perm:[1,0,3,2] row_mask:0xf bank_mask:0xf
	v_cndmask_b32_dpp v32, v24, v32, vcc quad_perm:[1,0,3,2] row_mask:0xf bank_mask:0xf
	v_cndmask_b32_dpp v33, v25, v33, vcc quad_perm:[1,0,3,2] row_mask:0xf bank_mask:0xf
	global_store_dwordx4 v208, v[30:33], s[64:65] nt
	global_store_dwordx4 v209, v[26:29], s[64:65] nt
	s_waitcnt lgkmcnt(0)
	s_add_u32 s64, s62, 0xd1000
	s_addc_u32 s65, s63, 0
	v_pk_mul_f32 v[14:15], v[14:15], v[206:207] op_sel_hi:[1,0]
	v_pk_mul_f32 v[16:17], v[16:17], v[206:207] op_sel_hi:[1,0]
	v_pk_mul_f32 v[10:11], v[10:11], v[206:207] op_sel_hi:[1,0]
	v_pk_mul_f32 v[12:13], v[12:13], v[206:207] op_sel_hi:[1,0]
	v_cvt_pk_bf16_f32 v14, v14, v15
	v_cvt_pk_bf16_f32 v15, v16, v17
	v_cvt_pk_bf16_f32 v16, v10, v11
	v_cvt_pk_bf16_f32 v17, v12, v13
	v_pk_mul_f32 v[6:7], v[6:7], v[206:207] op_sel_hi:[1,0]
	v_pk_mul_f32 v[8:9], v[8:9], v[206:207] op_sel_hi:[1,0]
	v_pk_mul_f32 v[2:3], v[2:3], v[206:207] op_sel_hi:[1,0]
	v_pk_mul_f32 v[4:5], v[4:5], v[206:207] op_sel_hi:[1,0]
	v_cvt_pk_bf16_f32 v6, v6, v7
	v_cvt_pk_bf16_f32 v7, v8, v9
	v_cvt_pk_bf16_f32 v8, v2, v3
	v_cvt_pk_bf16_f32 v9, v4, v5
	s_mov_b64 vcc, s[98:99]
	v_cndmask_b32_dpp v10, v14, v6, vcc quad_perm:[1,0,3,2] row_mask:0xf bank_mask:0xf
	v_cndmask_b32_dpp v11, v15, v7, vcc quad_perm:[1,0,3,2] row_mask:0xf bank_mask:0xf
	v_cndmask_b32_dpp v12, v16, v8, vcc quad_perm:[1,0,3,2] row_mask:0xf bank_mask:0xf
	v_cndmask_b32_dpp v13, v17, v9, vcc quad_perm:[1,0,3,2] row_mask:0xf bank_mask:0xf
	s_mov_b64 vcc, s[92:93]
	v_cndmask_b32_dpp v14, v6, v14, vcc quad_perm:[1,0,3,2] row_mask:0xf bank_mask:0xf
	v_cndmask_b32_dpp v15, v7, v15, vcc quad_perm:[1,0,3,2] row_mask:0xf bank_mask:0xf
	v_cndmask_b32_dpp v16, v8, v16, vcc quad_perm:[1,0,3,2] row_mask:0xf bank_mask:0xf
	v_cndmask_b32_dpp v17, v9, v17, vcc quad_perm:[1,0,3,2] row_mask:0xf bank_mask:0xf
	global_store_dwordx4 v208, v[14:17], s[64:65] nt
	global_store_dwordx4 v209, v[10:13], s[64:65] nt
	s_andn2_b64 vcc, exec, s[36:37]
	s_mov_b64 s[26:27], -1
	s_cbranch_vccnz .LBB0_105

; #define LAS __attribute__((address_space(3)))
; __device__ __forceinline__ float bf2f(bf16_t b) { return __uint_as_float((unsigned)b << 16); }
; __device__ __forceinline__ unsigned cvt_pk_bf16(float lo, float hi) { unsigned r; asm volatile("v_cvt_pk_bf16_f32 %0, %1, %2" : "=v"(r) : "v"(lo), "v"(hi)); return r; }
; __device__ __forceinline__ float gelu_tanh(float x) { const float y = 0.7978845608028654f * (x + 0.044715f * x * x * x); const float e = __expf(2.f * y); return 0.5f * x * (2.f - 2.f * __builtin_amdgcn_rcpf(1.f + e)); }
; __device__ __forceinline__ void lru_chain(unsigned char* ws_, const float* const* in_, int l_, LAS unsigned char* lds, int tid, int bid, int G) {
;     ...
;             for (int i = 0; i < 16; i += 2) { hh = av[i] * hh + bv[i]; const float h0 = hh; hh = av[i + 1] * hh + bv[i + 1]; const int tl = 16 * w + i;
;                 const float g0 = gelu_tanh(bf2f(*(const LAS bf16_t*)(GT + tl * 144 + lane * 2))), g1 = gelu_tanh(bf2f(*(const LAS bf16_t*)(GT + (tl + 1) * 144 + lane * 2)));
;                 const unsigned pk = cvt_pk_bf16(g0 * h0, g1 * hh);
;                 *(LAS bf16_t*)(OT + tl * 144 + lane * 2) = (bf16_t)(pk & 0xffffu); *(LAS bf16_t*)(OT + (tl + 1) * 144 + lane * 2) = (bf16_t)(pk >> 16); }
;             if (w == 7) CAR[((chunk + 1) & 1) * 64 + lane] = hh;
.LBB0_203:
	s_waitcnt lgkmcnt(0)
	ds_read_u16 v216, v204
	ds_read_u16 v217, v204 offset:144
	ds_read_u16 v218, v204 offset:288
	ds_read_u16 v219, v204 offset:432
	ds_read_u16 v220, v204 offset:576
	ds_read_u16 v221, v204 offset:720
	ds_read_u16 v222, v204 offset:864
	ds_read_u16 v223, v204 offset:1008
	ds_read_u16 v224, v204 offset:1152
	ds_read_u16 v225, v204 offset:1296
	ds_read_u16 v226, v204 offset:1440
	ds_read_u16 v227, v204 offset:1584
	ds_read_u16 v228, v204 offset:1728
	ds_read_u16 v229, v204 offset:1872
	ds_read_u16 v230, v204 offset:2016
	ds_read_u16 v231, v204 offset:2160
	s_and_b64 vcc, exec, s[50:51]
	s_mov_b32 s16, 0x3d372713
	s_mov_b32 s18, 0x3f4c422a
	s_mov_b32 s20, 0x3fb8aa3b
	s_mov_b32 s22, 0.5
	s_mov_b32 s6, 1.0
	s_mov_b32 s10, -2.0
	s_mov_b32 s100, 2.0
	s_waitcnt lgkmcnt(15)
	v_lshlrev_b32_e32 v216, 16, v216
	s_waitcnt lgkmcnt(14)
	v_lshlrev_b32_e32 v217, 16, v217
	s_waitcnt lgkmcnt(13)
	v_lshlrev_b32_e32 v218, 16, v218
	s_waitcnt lgkmcnt(12)
	v_lshlrev_b32_e32 v219, 16, v219
	s_waitcnt lgkmcnt(11)
	v_lshlrev_b32_e32 v220, 16, v220
	s_waitcnt lgkmcnt(10)
	v_lshlrev_b32_e32 v221, 16, v221
	s_waitcnt lgkmcnt(9)
	v_lshlrev_b32_e32 v222, 16, v222
	s_waitcnt lgkmcnt(8)
	v_lshlrev_b32_e32 v223, 16, v223
	s_waitcnt lgkmcnt(7)
	v_lshlrev_b32_e32 v224, 16, v224
	s_waitcnt lgkmcnt(6)
	v_lshlrev_b32_e32 v225, 16, v225
	s_waitcnt lgkmcnt(5)
	v_lshlrev_b32_e32 v226, 16, v226
	s_waitcnt lgkmcnt(4)
	v_lshlrev_b32_e32 v227, 16, v227
	s_waitcnt lgkmcnt(3)
	v_lshlrev_b32_e32 v228, 16, v228
	s_waitcnt lgkmcnt(2)
	v_lshlrev_b32_e32 v229, 16, v229
	s_waitcnt lgkmcnt(1)
	v_lshlrev_b32_e32 v230, 16, v230
	s_waitcnt lgkmcnt(0)
	v_lshlrev_b32_e32 v231, 16, v231
	v_fma_f32 v96, v100, v1, v96
	v_fmac_f32_e32 v97, v101, v96
	v_pk_mul_f32 v[234:235], v[216:217], s[16:17] op_sel_hi:[1,0]
	v_pk_mul_f32 v[236:237], v[218:219], s[16:17] op_sel_hi:[1,0]
	v_pk_mul_f32 v[238:239], v[220:221], s[16:17] op_sel_hi:[1,0]
	v_pk_mul_f32 v[240:241], v[222:223], s[16:17] op_sel_hi:[1,0]
	v_pk_mul_f32 v[242:243], v[224:225], s[16:17] op_sel_hi:[1,0]
	v_pk_mul_f32 v[244:245], v[226:227], s[16:17] op_sel_hi:[1,0]
	v_pk_mul_f32 v[246:247], v[228:229], s[16:17] op_sel_hi:[1,0]
	v_pk_mul_f32 v[248:249], v[230:231], s[16:17] op_sel_hi:[1,0]
	v_fmac_f32_e32 v92, v98, v97
	v_fmac_f32_e32 v93, v99, v92
	v_pk_mul_f32 v[234:235], v[234:235], v[216:217]
	v_pk_mul_f32 v[236:237], v[236:237], v[218:219]
	v_pk_mul_f32 v[238:239], v[238:239], v[220:221]
	v_pk_mul_f32 v[240:241], v[240:241], v[222:223]
	v_pk_mul_f32 v[242:243], v[242:243], v[224:225]
	v_pk_mul_f32 v[244:245], v[244:245], v[226:227]
	v_pk_mul_f32 v[246:247], v[246:247], v[228:229]
	v_pk_mul_f32 v[248:249], v[248:249], v[230:231]
	v_fmac_f32_e32 v88, v94, v93
	v_fmac_f32_e32 v89, v95, v88
	v_pk_fma_f32 v[234:235], v[234:235], v[216:217], v[216:217]
	v_pk_fma_f32 v[236:237], v[236:237], v[218:219], v[218:219]
	v_pk_fma_f32 v[238:239], v[238:239], v[220:221], v[220:221]
	v_pk_fma_f32 v[240:241], v[240:241], v[222:223], v[222:223]
	v_pk_fma_f32 v[242:243], v[242:243], v[224:225], v[224:225]
	v_pk_fma_f32 v[244:245], v[244:245], v[226:227], v[226:227]
	v_pk_fma_f32 v[246:247], v[246:247], v[228:229], v[228:229]
	v_pk_fma_f32 v[248:249], v[248:249], v[230:231], v[230:231]
	v_fmac_f32_e32 v84, v90, v89
	v_fmac_f32_e32 v85, v91, v84
	v_pk_mul_f32 v[234:235], v[234:235], s[18:19] op_sel_hi:[1,0]
	v_pk_mul_f32 v[236:237], v[236:237], s[18:19] op_sel_hi:[1,0]
	v_pk_mul_f32 v[238:239], v[238:239], s[18:19] op_sel_hi:[1,0]
	v_pk_mul_f32 v[240:241], v[240:241], s[18:19] op_sel_hi:[1,0]
	v_pk_mul_f32 v[242:243], v[242:243], s[18:19] op_sel_hi:[1,0]
	v_pk_mul_f32 v[244:245], v[244:245], s[18:19] op_sel_hi:[1,0]
	v_pk_mul_f32 v[246:247], v[246:247], s[18:19] op_sel_hi:[1,0]
	v_pk_mul_f32 v[248:249], v[248:249], s[18:19] op_sel_hi:[1,0]
	v_fmac_f32_e32 v80, v86, v85
	v_fmac_f32_e32 v81, v87, v80
	v_pk_add_f32 v[234:235], v[234:235], v[234:235]
	v_pk_add_f32 v[236:237], v[236:237], v[236:237]
	v_pk_add_f32 v[238:239], v[238:239], v[238:239]
	v_pk_add_f32 v[240:241], v[240:241], v[240:241]
	v_pk_add_f32 v[242:243], v[242:243], v[242:243]
	v_pk_add_f32 v[244:245], v[244:245], v[244:245]
	v_pk_add_f32 v[246:247], v[246:247], v[246:247]
	v_pk_add_f32 v[248:249], v[248:249], v[248:249]
	v_fmac_f32_e32 v76, v82, v81
	v_fmac_f32_e32 v77, v83, v76
	v_pk_mul_f32 v[234:235], v[234:235], s[20:21] op_sel_hi:[1,0]
	v_pk_mul_f32 v[236:237], v[236:237], s[20:21] op_sel_hi:[1,0]
	v_pk_mul_f32 v[238:239], v[238:239], s[20:21] op_sel_hi:[1,0]
	v_pk_mul_f32 v[240:241], v[240:241], s[20:21] op_sel_hi:[1,0]
; #define LAS __attribute__((address_space(3)))
; __device__ __forceinline__ float bf2f(bf16_t b) { return __uint_as_float((unsigned)b << 16); }
; __device__ __forceinline__ unsigned cvt_pk_bf16(float lo, float hi) { unsigned r; asm volatile("v_cvt_pk_bf16_f32 %0, %1, %2" : "=v"(r) : "v"(lo), "v"(hi)); return r; }
; __device__ __forceinline__ float gelu_tanh(float x) { const float y = 0.7978845608028654f * (x + 0.044715f * x * x * x); const float e = __expf(2.f * y); return 0.5f * x * (2.f - 2.f * __builtin_amdgcn_rcpf(1.f + e)); }
; __device__ __forceinline__ void lru_chain(unsigned char* ws_, const float* const* in_, int l_, LAS unsigned char* lds, int tid, int bid, int G) {
;     ...
;             for (int i = 0; i < 16; i += 2) { hh = av[i] * hh + bv[i]; const float h0 = hh; hh = av[i + 1] * hh + bv[i + 1]; const int tl = 16 * w + i;
;                 const float g0 = gelu_tanh(bf2f(*(const LAS bf16_t*)(GT + tl * 144 + lane * 2))), g1 = gelu_tanh(bf2f(*(const LAS bf16_t*)(GT + (tl + 1) * 144 + lane * 2)));
;                 const unsigned pk = cvt_pk_bf16(g0 * h0, g1 * hh);
;                 *(LAS bf16_t*)(OT + tl * 144 + lane * 2) = (bf16_t)(pk & 0xffffu); *(LAS bf16_t*)(OT + (tl + 1) * 144 + lane * 2) = (bf16_t)(pk >> 16); }
	v_pk_mul_f32 v[242:243], v[242:243], s[20:21] op_sel_hi:[1,0]
	v_pk_mul_f32 v[244:245], v[244:245], s[20:21] op_sel_hi:[1,0]
	v_pk_mul_f32 v[246:247], v[246:247], s[20:21] op_sel_hi:[1,0]
	v_pk_mul_f32 v[248:249], v[248:249], s[20:21] op_sel_hi:[1,0]
	v_fmac_f32_e32 v72, v78, v77
	v_fmac_f32_e32 v73, v79, v72
	v_exp_f32_e32 v234, v234
	v_exp_f32_e32 v235, v235
	v_exp_f32_e32 v236, v236
	v_exp_f32_e32 v237, v237
	v_exp_f32_e32 v238, v238
	v_exp_f32_e32 v239, v239
	v_exp_f32_e32 v240, v240
	v_exp_f32_e32 v241, v241
	v_exp_f32_e32 v242, v242
	v_exp_f32_e32 v243, v243
	v_exp_f32_e32 v244, v244
	v_exp_f32_e32 v245, v245
	v_exp_f32_e32 v246, v246
	v_exp_f32_e32 v247, v247
	v_exp_f32_e32 v248, v248
	v_exp_f32_e32 v249, v249
	v_fmac_f32_e32 v2, v74, v73
	v_fmac_f32_e32 v3, v75, v2
	v_pk_mul_f32 v[216:217], v[216:217], s[22:23] op_sel_hi:[1,0]
	v_pk_mul_f32 v[218:219], v[218:219], s[22:23] op_sel_hi:[1,0]
	v_pk_mul_f32 v[220:221], v[220:221], s[22:23] op_sel_hi:[1,0]
	v_pk_mul_f32 v[222:223], v[222:223], s[22:23] op_sel_hi:[1,0]
	v_pk_mul_f32 v[224:225], v[224:225], s[22:23] op_sel_hi:[1,0]
	v_pk_mul_f32 v[226:227], v[226:227], s[22:23] op_sel_hi:[1,0]
	v_pk_mul_f32 v[228:229], v[228:229], s[22:23] op_sel_hi:[1,0]
	v_pk_mul_f32 v[230:231], v[230:231], s[22:23] op_sel_hi:[1,0]
	v_pk_add_f32 v[234:235], v[234:235], s[6:7] op_sel_hi:[1,0]
	v_pk_add_f32 v[236:237], v[236:237], s[6:7] op_sel_hi:[1,0]
	v_pk_add_f32 v[238:239], v[238:239], s[6:7] op_sel_hi:[1,0]
	v_pk_add_f32 v[240:241], v[240:241], s[6:7] op_sel_hi:[1,0]
	v_pk_add_f32 v[242:243], v[242:243], s[6:7] op_sel_hi:[1,0]
	v_pk_add_f32 v[244:245], v[244:245], s[6:7] op_sel_hi:[1,0]
	v_pk_add_f32 v[246:247], v[246:247], s[6:7] op_sel_hi:[1,0]
	v_pk_add_f32 v[248:249], v[248:249], s[6:7] op_sel_hi:[1,0]
	v_rcp_f32_e32 v234, v234
	v_rcp_f32_e32 v235, v235
	v_rcp_f32_e32 v236, v236
	v_rcp_f32_e32 v237, v237
	v_rcp_f32_e32 v238, v238
	v_rcp_f32_e32 v239, v239
	v_rcp_f32_e32 v240, v240
	v_rcp_f32_e32 v241, v241
	v_rcp_f32_e32 v242, v242
	v_rcp_f32_e32 v243, v243
	v_rcp_f32_e32 v244, v244
	v_rcp_f32_e32 v245, v245
	v_rcp_f32_e32 v246, v246
	v_rcp_f32_e32 v247, v247
	v_rcp_f32_e32 v248, v248
	v_rcp_f32_e32 v249, v249
	v_fma_f32 v234, v234, -2.0, 2.0
	v_fma_f32 v235, v235, -2.0, 2.0
	v_fma_f32 v236, v236, -2.0, 2.0
	v_fma_f32 v237, v237, -2.0, 2.0
	v_fma_f32 v238, v238, -2.0, 2.0
	v_fma_f32 v239, v239, -2.0, 2.0
	v_fma_f32 v240, v240, -2.0, 2.0
	v_fma_f32 v241, v241, -2.0, 2.0
	v_fma_f32 v242, v242, -2.0, 2.0
	v_fma_f32 v243, v243, -2.0, 2.0
	v_fma_f32 v244, v244, -2.0, 2.0
	v_fma_f32 v245, v245, -2.0, 2.0
	v_fma_f32 v246, v246, -2.0, 2.0
	v_fma_f32 v247, v247, -2.0, 2.0
	v_fma_f32 v248, v248, -2.0, 2.0
	v_fma_f32 v249, v249, -2.0, 2.0
	v_pk_mul_f32 v[216:217], v[216:217], v[234:235]
	v_pk_mul_f32 v[218:219], v[218:219], v[236:237]
	v_pk_mul_f32 v[220:221], v[220:221], v[238:239]
	v_pk_mul_f32 v[222:223], v[222:223], v[240:241]
	v_pk_mul_f32 v[224:225], v[224:225], v[242:243]
	v_pk_mul_f32 v[226:227], v[226:227], v[244:245]
	v_pk_mul_f32 v[228:229], v[228:229], v[246:247]
	v_pk_mul_f32 v[230:231], v[230:231], v[248:249]
	v_pk_mul_f32 v[234:235], v[96:97], v[216:217]
	v_pk_mul_f32 v[236:237], v[92:93], v[218:219]
	v_pk_mul_f32 v[238:239], v[88:89], v[220:221]
	v_pk_mul_f32 v[240:241], v[84:85], v[222:223]
	v_pk_mul_f32 v[242:243], v[80:81], v[224:225]
	v_pk_mul_f32 v[244:245], v[76:77], v[226:227]
	v_pk_mul_f32 v[246:247], v[72:73], v[228:229]
	v_pk_mul_f32 v[248:249], v[2:3], v[230:231]
	v_cvt_pk_bf16_f32 v216, v234, v235
	v_cvt_pk_bf16_f32 v217, v236, v237
	v_cvt_pk_bf16_f32 v218, v238, v239
	v_cvt_pk_bf16_f32 v219, v240, v241
	v_cvt_pk_bf16_f32 v220, v242, v243
	v_cvt_pk_bf16_f32 v221, v244, v245
	v_cvt_pk_bf16_f32 v222, v246, v247
	v_cvt_pk_bf16_f32 v223, v248, v249
	ds_write_b16 v205, v216 offset:18432
	ds_write_b16_d16_hi v205, v216 offset:18576
	ds_write_b16 v205, v217 offset:18720
	ds_write_b16_d16_hi v205, v217 offset:18864
	ds_write_b16 v205, v218 offset:19008
	ds_write_b16_d16_hi v205, v218 offset:19152
	ds_write_b16 v205, v219 offset:19296
	ds_write_b16_d16_hi v205, v219 offset:19440
	ds_write_b16 v205, v220 offset:19584
	ds_write_b16_d16_hi v205, v220 offset:19728
	ds_write_b16 v205, v221 offset:19872
	ds_write_b16_d16_hi v205, v221 offset:20016
	ds_write_b16 v205, v222 offset:20160
	ds_write_b16_d16_hi v205, v222 offset:20304
	ds_write_b16 v205, v223 offset:20448
	ds_write_b16_d16_hi v205, v223 offset:20592
	s_cbranch_vccz .LBB0_186
	v_bitop3_b32 v1, s2, 64, v151 bitop3:0x36
	v_lshl_add_u32 v1, v1, 2, 0
	v_add_u32_e32 v1, 0x1fb00, v1
	ds_write_b32 v1, v3
	s_branch .LBB0_186

; __device__ __forceinline__ float bf_lo(unsigned w) { return __uint_as_float(w << 16); }
; __device__ __forceinline__ float bf_hi(unsigned w) { return __uint_as_float(w & 0xffff0000u); }
; __device__ __forceinline__ unsigned pk2(float lo, float hi) { return f2bf(lo) | (f2bf(hi) << 16); }
; __device__ __forceinline__ void alpha_phase(const Ctx& C) {
;     ...
;     for (int tg = gw; tg < M / 4; tg += NGW) {
; #pragma unroll
;         for (int i = 0; i < 3; ++i) { const int L = C.lane + 64 * i; const size_t tok = (size_t)4 * tg + L / 48; const int ch = L % 48, h = ch >> 3, jj = h & 1, g = h >> 1;
;             const float l0 = LSE[tok * 6 + jj], l1 = LSE[tok * 6 + 2 + jj], l2 = LSE[tok * 6 + 4 + jj];
;             const float mx = fmaxf(l0, fmaxf(l1, l2)); const float e0 = __expf(l0 - mx), e1 = __expf(l1 - mx), e2 = __expf(l2 - mx);
;             const float al = (g == 0 ? e0 : (g == 1 ? e1 : e2)) / (e0 + e1 + e2);
;             const u32x4 v = *(const u32x4*)(AO + tok * AW + ch * 8); u32x4 o;
;             o.x = pk2(bf_lo(v.x) * al, bf_hi(v.x) * al); o.y = pk2(bf_lo(v.y) * al, bf_hi(v.y) * al); o.z = pk2(bf_lo(v.z) * al, bf_hi(v.z) * al); o.w = pk2(bf_lo(v.w) * al, bf_hi(v.w) * al);
;             *(u32x4*)(MIX + tok * DM + ch * 8) = o; }
.LBB0_359:
	v_lshl_add_u64 v[60:61], v[12:13], 0, s[28:29]
	global_load_dword v72, v[60:61], off offset:-8
	global_load_dword v62, v[60:61], off
	global_load_dword v60, v[60:61], off offset:8
	s_add_i32 s2, s2, s10
	v_lshl_add_u64 v[12:13], v[12:13], 0, s[34:35]
	s_cmpk_lt_i32 s2, 0x4000
	v_lshl_add_u64 v[76:77], v[14:15], 0, s[28:29]
	global_load_dword v88, v[76:77], off offset:-8
	global_load_dword v78, v[76:77], off
	global_load_dword v76, v[76:77], off offset:8
	v_lshl_add_u64 v[14:15], v[14:15], 0, s[34:35]
	v_lshl_add_u64 v[92:93], v[4:5], 0, s[28:29]
	global_load_dword v104, v[92:93], off offset:-8
	global_load_dword v94, v[92:93], off
	global_load_dword v92, v[92:93], off offset:8
	v_lshl_add_u64 v[4:5], v[4:5], 0, s[34:35]
	s_waitcnt vmcnt(0)
	v_max3_f32 v61, v72, v62, v60
	v_sub_f32_e32 v62, v62, v61
	v_sub_f32_e32 v60, v60, v61
	v_sub_f32_e32 v72, v72, v61
	v_mul_f32_e32 v62, 0x3fb8aa3b, v62
	v_mul_f32_e32 v60, 0x3fb8aa3b, v60
	v_mul_f32_e32 v72, 0x3fb8aa3b, v72
	v_exp_f32_e32 v62, v62
	v_exp_f32_e32 v60, v60
	v_exp_f32_e32 v72, v72
	v_cndmask_b32_e64 v61, v60, v62, s[38:39]
	v_cndmask_b32_e64 v61, v61, v72, s[36:37]
	v_add_f32_e32 v72, v72, v62
	v_add_f32_e32 v72, v60, v72
	v_div_scale_f32 v60, s[4:5], v72, v72, v61
	v_rcp_f32_e32 v62, v60
	s_nop 0
	v_fma_f32 v63, -v60, v62, 1.0
	v_fmac_f32_e32 v62, v63, v62
	v_div_scale_f32 v63, vcc, v61, v72, v61
	v_mul_f32_e32 v64, v63, v62
	v_fma_f32 v65, -v60, v64, v63
	v_fmac_f32_e32 v64, v65, v62
	v_fma_f32 v60, -v60, v64, v63
	v_div_fmas_f32 v60, v60, v62, v64
	v_div_fixup_f32 v64, v60, v72, v61
	v_max3_f32 v77, v88, v78, v76
	v_sub_f32_e32 v78, v78, v77
	v_sub_f32_e32 v76, v76, v77
	v_sub_f32_e32 v88, v88, v77
	v_mul_f32_e32 v78, 0x3fb8aa3b, v78
	v_mul_f32_e32 v76, 0x3fb8aa3b, v76
	v_mul_f32_e32 v88, 0x3fb8aa3b, v88
	v_exp_f32_e32 v78, v78
	v_exp_f32_e32 v76, v76
	v_exp_f32_e32 v88, v88
	v_cndmask_b32_e64 v77, v76, v78, s[42:43]
	v_cndmask_b32_e64 v77, v77, v88, s[40:41]
	v_add_f32_e32 v88, v88, v78
	v_add_f32_e32 v88, v76, v88
	v_div_scale_f32 v76, s[4:5], v88, v88, v77
	v_rcp_f32_e32 v78, v76
	s_nop 0
	v_fma_f32 v79, -v76, v78, 1.0
	v_fmac_f32_e32 v78, v79, v78
	v_div_scale_f32 v79, vcc, v77, v88, v77
	v_mul_f32_e32 v80, v79, v78
	v_fma_f32 v81, -v76, v80, v79
	v_fmac_f32_e32 v80, v81, v78
	v_fma_f32 v76, -v76, v80, v79
	v_div_fmas_f32 v76, v76, v78, v80
	v_div_fixup_f32 v80, v76, v88, v77
	v_max3_f32 v93, v104, v94, v92
	v_sub_f32_e32 v94, v94, v93
	v_sub_f32_e32 v92, v92, v93
	v_sub_f32_e32 v104, v104, v93
	v_mul_f32_e32 v94, 0x3fb8aa3b, v94
	v_mul_f32_e32 v92, 0x3fb8aa3b, v92
	v_mul_f32_e32 v104, 0x3fb8aa3b, v104
	v_exp_f32_e32 v94, v94
	v_exp_f32_e32 v92, v92
	v_exp_f32_e32 v104, v104
	v_cndmask_b32_e64 v93, v92, v94, s[46:47]
	v_cndmask_b32_e64 v93, v93, v104, s[44:45]
	v_add_f32_e32 v104, v104, v94
	v_add_f32_e32 v104, v92, v104
	v_div_scale_f32 v92, s[4:5], v104, v104, v93
	v_rcp_f32_e32 v94, v92
	s_nop 0
	v_fma_f32 v95, -v92, v94, 1.0
	v_fmac_f32_e32 v94, v95, v94
	v_div_scale_f32 v95, vcc, v93, v104, v93
	v_mul_f32_e32 v96, v95, v94
	v_fma_f32 v97, -v92, v96, v95
	v_fmac_f32_e32 v96, v97, v94
	v_fma_f32 v92, -v92, v96, v95
	v_div_fmas_f32 v92, v92, v94, v96
	v_lshl_add_u64 v[60:61], v[6:7], 0, s[28:29]
	global_load_dwordx4 v[60:63], v[60:61], off
	v_lshl_add_u64 v[6:7], v[6:7], 0, s[30:31]
	v_lshl_add_u64 v[76:77], v[18:19], 0, s[28:29]
	global_load_dwordx4 v[76:79], v[76:77], off
	v_lshl_add_u64 v[18:19], v[18:19], 0, s[30:31]
	v_lshl_add_u64 v[94:95], v[8:9], 0, s[28:29]
	global_load_dwordx4 v[94:97], v[94:95], off
	v_div_fixup_f32 v92, v92, v104, v93
	v_lshl_add_u64 v[8:9], v[8:9], 0, s[30:31]
	s_waitcnt vmcnt(0)
; __device__ __forceinline__ float bf_lo(unsigned w) { return __uint_as_float(w << 16); }
; __device__ __forceinline__ float bf_hi(unsigned w) { return __uint_as_float(w & 0xffff0000u); }
; __device__ __forceinline__ unsigned pk2(float lo, float hi) { return f2bf(lo) | (f2bf(hi) << 16); }
; __device__ __forceinline__ void alpha_phase(const Ctx& C) {
;     ...
;             const u32x4 v = *(const u32x4*)(AO + tok * AW + ch * 8); u32x4 o;
;             o.x = pk2(bf_lo(v.x) * al, bf_hi(v.x) * al); o.y = pk2(bf_lo(v.y) * al, bf_hi(v.y) * al); o.z = pk2(bf_lo(v.z) * al, bf_hi(v.z) * al); o.w = pk2(bf_lo(v.w) * al, bf_hi(v.w) * al);
;             *(u32x4*)(MIX + tok * DM + ch * 8) = o; }
	v_lshlrev_b32_e32 v67, 16, v61
	v_lshlrev_b32_e32 v66, 16, v60
	v_and_b32_e32 v61, 0xffff0000, v61
	v_and_b32_e32 v60, 0xffff0000, v60
	v_lshlrev_b32_e32 v69, 16, v63
	v_lshlrev_b32_e32 v68, 16, v62
	v_and_b32_e32 v63, 0xffff0000, v63
	v_and_b32_e32 v62, 0xffff0000, v62
	v_pk_mul_f32 v[60:61], v[64:65], v[60:61] op_sel_hi:[0,1]
	v_pk_mul_f32 v[62:63], v[64:65], v[62:63] op_sel_hi:[0,1]
	v_pk_mul_f32 v[66:67], v[64:65], v[66:67] op_sel_hi:[0,1]
	v_pk_mul_f32 v[68:69], v[64:65], v[68:69] op_sel_hi:[0,1]
	v_bfe_u32 v72, v63, 16, 1
	v_bfe_u32 v64, v62, 16, 1
	v_bfe_u32 v65, v61, 16, 1
	v_bfe_u32 v70, v60, 16, 1
	v_add3_u32 v60, v60, v70, s94
	v_add3_u32 v61, v61, v65, s94
	v_add3_u32 v62, v62, v64, s94
	v_add3_u32 v72, v63, v72, s94
	v_bfe_u32 v63, v66, 16, 1
	v_bfe_u32 v64, v67, 16, 1
	v_bfe_u32 v65, v68, 16, 1
	v_bfe_u32 v70, v69, 16, 1
	v_add3_u32 v69, v69, v70, s94
	v_add3_u32 v65, v68, v65, s94
	v_add3_u32 v64, v67, v64, s94
	v_add3_u32 v63, v66, v63, s94
	v_lshrrev_b32_e32 v66, 16, v63
	v_lshrrev_b32_e32 v64, 16, v64
	v_lshrrev_b32_e32 v65, 16, v65
	v_lshrrev_b32_e32 v63, 16, v69
	v_and_or_b32 v63, v72, s88, v63
	v_and_or_b32 v62, v62, s88, v65
	v_and_or_b32 v61, v61, s88, v64
	v_and_or_b32 v60, v60, s88, v66
	v_lshl_add_u64 v[64:65], v[2:3], 0, s[28:29]
	global_store_dwordx4 v[64:65], v[60:63], off
	v_lshl_add_u64 v[2:3], v[2:3], 0, s[24:25]
	s_nop 0
	v_lshlrev_b32_e32 v83, 16, v77
	v_lshlrev_b32_e32 v82, 16, v76
	v_and_b32_e32 v77, 0xffff0000, v77
	v_and_b32_e32 v76, 0xffff0000, v76
	v_lshlrev_b32_e32 v85, 16, v79
	v_lshlrev_b32_e32 v84, 16, v78
	v_and_b32_e32 v79, 0xffff0000, v79
	v_and_b32_e32 v78, 0xffff0000, v78
	v_pk_mul_f32 v[76:77], v[80:81], v[76:77] op_sel_hi:[0,1]
	v_pk_mul_f32 v[78:79], v[80:81], v[78:79] op_sel_hi:[0,1]
	v_pk_mul_f32 v[82:83], v[80:81], v[82:83] op_sel_hi:[0,1]
	v_pk_mul_f32 v[84:85], v[80:81], v[84:85] op_sel_hi:[0,1]
	v_bfe_u32 v88, v79, 16, 1
	v_bfe_u32 v80, v78, 16, 1
	v_bfe_u32 v81, v77, 16, 1
	v_bfe_u32 v86, v76, 16, 1
	v_add3_u32 v76, v76, v86, s94
	v_add3_u32 v77, v77, v81, s94
	v_add3_u32 v78, v78, v80, s94
	v_add3_u32 v88, v79, v88, s94
	v_bfe_u32 v79, v82, 16, 1
	v_bfe_u32 v80, v83, 16, 1
	v_bfe_u32 v81, v84, 16, 1
	v_bfe_u32 v86, v85, 16, 1
	v_add3_u32 v85, v85, v86, s94
	v_add3_u32 v81, v84, v81, s94
	v_add3_u32 v80, v83, v80, s94
	v_add3_u32 v79, v82, v79, s94
	v_lshrrev_b32_e32 v82, 16, v79
	v_lshrrev_b32_e32 v80, 16, v80
	v_lshrrev_b32_e32 v81, 16, v81
	v_lshrrev_b32_e32 v79, 16, v85
	v_and_or_b32 v79, v88, s88, v79
	v_and_or_b32 v78, v78, s88, v81
	v_and_or_b32 v77, v77, s88, v80
	v_and_or_b32 v76, v76, s88, v82
	v_lshl_add_u64 v[80:81], v[16:17], 0, s[28:29]
	global_store_dwordx4 v[80:81], v[76:79], off
	v_lshl_add_u64 v[16:17], v[16:17], 0, s[24:25]
	s_nop 0
	v_lshlrev_b32_e32 v99, 16, v95
	v_lshlrev_b32_e32 v98, 16, v94
	v_and_b32_e32 v95, 0xffff0000, v95
	v_and_b32_e32 v94, 0xffff0000, v94
	v_lshlrev_b32_e32 v101, 16, v97
	v_lshlrev_b32_e32 v100, 16, v96
	v_and_b32_e32 v97, 0xffff0000, v97
	v_and_b32_e32 v96, 0xffff0000, v96
	v_pk_mul_f32 v[98:99], v[92:93], v[98:99] op_sel_hi:[0,1]
	v_pk_mul_f32 v[94:95], v[92:93], v[94:95] op_sel_hi:[0,1]
	v_pk_mul_f32 v[100:101], v[92:93], v[100:101] op_sel_hi:[0,1]
	v_pk_mul_f32 v[92:93], v[92:93], v[96:97] op_sel_hi:[0,1]
	v_bfe_u32 v104, v93, 16, 1
	v_bfe_u32 v96, v92, 16, 1
	v_bfe_u32 v97, v95, 16, 1
	v_bfe_u32 v102, v94, 16, 1
	v_add3_u32 v102, v94, v102, s94
	v_add3_u32 v97, v95, v97, s94
	v_add3_u32 v92, v92, v96, s94
	v_add3_u32 v104, v93, v104, s94
	v_bfe_u32 v93, v98, 16, 1
	v_bfe_u32 v94, v99, 16, 1
	v_bfe_u32 v95, v100, 16, 1
	v_bfe_u32 v96, v101, 16, 1
	v_add3_u32 v96, v101, v96, s94
	v_add3_u32 v95, v100, v95, s94
	v_add3_u32 v94, v99, v94, s94
	v_add3_u32 v93, v98, v93, s94
	v_lshrrev_b32_e32 v98, 16, v93
	v_lshrrev_b32_e32 v93, 16, v94
	v_lshrrev_b32_e32 v94, 16, v95
	v_lshrrev_b32_e32 v95, 16, v96
	v_and_or_b32 v95, v104, s88, v95
	v_and_or_b32 v94, v92, s88, v94
	v_and_or_b32 v93, v97, s88, v93
	v_and_or_b32 v92, v102, s88, v98
	v_lshl_add_u64 v[96:97], v[10:11], 0, s[28:29]
	v_lshl_add_u64 v[10:11], v[10:11], 0, s[24:25]
	global_store_dwordx4 v[96:97], v[92:95], off
	s_cbranch_scc1 .LBB0_359
	v_readlane_b32 s6, v255, 49
	v_readlane_b32 s46, v255, 51
	v_readlane_b32 s48, v253, 47
	v_readlane_b32 s7, v255, 50
	v_readlane_b32 s47, v255, 52
	v_readlane_b32 s49, v253, 48

; #define LAS __attribute__((address_space(3)))
; __device__ __forceinline__ unsigned cvt_pk_bf16(float lo, float hi) { unsigned r; asm volatile("v_cvt_pk_bf16_f32 %0, %1, %2" : "=v"(r) : "v"(lo), "v"(hi)); return r; }
; __device__ __forceinline__ float rinv_from(u64 v) { return rsqrtf((float)v * (1.0f / 16777216.0f) * (1.0f / 1024.0f) + RMS_EPS); }
;     __device__ __forceinline__ void operator()(const f32x4 (&acc)[2][2][4][2], const Unit& u, int wr, int wc, int fr, int fq) const {
;         const int ln = fr + 16 * fq; const int colw = u.pn * BM + 64 * wc;
;         if (colw >= nvalid) return;
;         float rl[2];
; #pragma unroll
;         for (int ai = 0; ai < 2; ++ai) rl[ai] = rinv_from(ssq[u.pm * BM + ai * HALF + wr * 64 + ln]);
;         LAS unsigned char* sl = stg + (wr * 4 + wc) * EPI_STG_SLICE;
;         const int rr = ln >> 3, cc = ln & 7;
; #pragma unroll
;         for (int ai = 0; ai < 2; ++ai)
; #pragma unroll
;             for (int m = 0; m < 4; ++m) {
;                 const float sc = __shfl(rl[ai], 16 * m + fr);
; #pragma unroll
;                 for (int bj = 0; bj < 2; ++bj) {
;                     f32x4 v0 = acc[ai][bj][m][0] * sc, v1 = acc[ai][bj][m][1] * sc;
;                     if (ACT == 1) {
; #pragma unroll
;                         for (int e = 0; e < 4; ++e) { float a = fmaxf(v0[e], 0.f), b = fmaxf(v1[e], 0.f); v0[e] = a * a; v1[e] = b * b; }
;                     }
;                     u32x4 w; w.x = cvt_pk_bf16(v0[0], v0[1]); w.y = cvt_pk_bf16(v0[2], v0[3]); w.z = cvt_pk_bf16(v1[0], v1[1]); w.w = cvt_pk_bf16(v1[2], v1[3]);
;                     *(LAS u32x4*)(sl + fr * 144 + bj * 64 + fq * 16) = w;
;                 }
;                 const int rowb = u.pm * BM + ai * HALF + wr * 64 + m * 16;
; #pragma unroll
;                 for (int i = 0; i < 2; ++i) { const int r = rr + 8 * i; const u32x4 q = *(const LAS u32x4*)(sl + r * 144 + cc * 16);
;                     __builtin_nontemporal_store(q, (u32x4*)(O + (size_t)(rowb + r) * ldc + colw + cc * 8)); }
.LBB0_519:
	s_lshl_b32 s2, s2, 8
	s_add_i32 s2, s2, s79
	v_or_b32_e32 v162, s2, v155
	v_ashrrev_i32_e32 v163, 31, v162
	v_lshl_add_u64 v[162:163], v[162:163], 3, s[28:29]
	v_mov_b32_e32 v164, v156
	v_mov_b32_e32 v165, v157
	s_nop 0
	v_mov_b32_e32 v162, v159
	s_mov_b32 s4, 0x33800000
	s_ashr_i32 s27, s26, 31
	s_or_b32 s3, s2, 16
	v_mov_b32_e32 v163, v160
	v_ffbh_u32_e32 v153, v165
	v_min_u32_e32 v153, 32, v153
	v_lshlrev_b64 v[164:165], v153, v[164:165]
	v_min_u32_e32 v161, 1, v164
	v_or_b32_e32 v161, v165, v161
	v_cvt_f32_u32_e32 v161, v161
	v_sub_u32_e32 v153, 32, v153
	v_ldexp_f32 v165, v161, v153
	v_ffbh_u32_e32 v153, v163
	v_min_u32_e32 v153, 32, v153
	v_lshlrev_b64 v[162:163], v153, v[162:163]
	v_min_u32_e32 v161, 1, v162
	v_or_b32_e32 v161, v163, v161
	v_cvt_f32_u32_e32 v161, v161
	v_sub_u32_e32 v153, 32, v153
	v_ldexp_f32 v164, v161, v153
	v_pk_mul_f32 v[162:163], v[164:165], s[4:5] op_sel_hi:[1,0]
	s_mov_b32 s4, 0x3a800000
	v_pk_fma_f32 v[162:163], v[162:163], s[4:5], v[138:139] op_sel_hi:[1,0,0]
	s_nop 0
	v_mul_f32_e32 v153, 0x4b800000, v163
	v_cmp_gt_f32_e64 s[40:41], s70, v163
	v_cmp_gt_f32_e32 vcc, s70, v162
	s_nop 0
	v_cndmask_b32_e64 v153, v163, v153, s[40:41]
	v_rsq_f32_e32 v153, v153
	s_nop 0
	v_mul_f32_e32 v161, 0x45800000, v153
	v_cndmask_b32_e64 v163, v153, v161, s[40:41]
	v_mul_f32_e32 v153, 0x4b800000, v162
	v_cndmask_b32_e32 v153, v162, v153, vcc
	v_rsq_f32_e32 v153, v153
	s_lshl_b64 s[40:41], s[26:27], 1
	v_mul_f32_e32 v161, 0x45800000, v153
	v_cndmask_b32_e32 v161, v153, v161, vcc
	v_and_or_b32 v153, v177, 64, v1
	v_lshlrev_b32_e32 v162, 2, v153
	ds_bpermute_b32 v192, v162, v163
	ds_bpermute_b32 v194, v162, v163 offset:64
	ds_bpermute_b32 v196, v162, v163 offset:128
	ds_bpermute_b32 v198, v162, v163 offset:192
	ds_bpermute_b32 v200, v162, v161
	ds_bpermute_b32 v202, v162, v161 offset:64
	ds_bpermute_b32 v204, v162, v161 offset:128
	ds_bpermute_b32 v206, v162, v161 offset:192
	v_and_b32_e32 v210, 1, v177
	v_and_b32_e32 v211, 14, v177
	v_cmp_eq_u32_e64 s[92:93], 0, v210
	v_cmp_ne_u32_e64 s[98:99], 0, v210
	v_lshlrev_b32_e32 v208, 13, v211
	s_lshl_b32 s7, s2, 13
	v_lshl_add_u32 v208, v210, 6, v208
	v_bfe_u32 v211, v177, 4, 2
	v_lshl_add_u32 v208, v211, 4, v208
	v_add_u32_e32 v209, 0x2000, v208
	s_add_u32 s62, s44, s7
	s_addc_u32 s63, s45, 0
	s_lshl_b32 s7, s26, 1
	s_add_u32 s62, s62, s7
	s_addc_u32 s63, s63, 0
	s_waitcnt lgkmcnt(7)
	s_mov_b32 s64, s62
	s_mov_b32 s65, s63
	v_pk_mul_f32 v[126:127], v[126:127], v[192:193] op_sel_hi:[1,0]
	v_pk_mul_f32 v[128:129], v[128:129], v[192:193] op_sel_hi:[1,0]
	v_pk_mul_f32 v[122:123], v[122:123], v[192:193] op_sel_hi:[1,0]
	v_pk_mul_f32 v[124:125], v[124:125], v[192:193] op_sel_hi:[1,0]
	v_max_f32_e32 v126, 0, v126
	v_max_f32_e32 v127, 0, v127
	v_max_f32_e32 v128, 0, v128
	v_max_f32_e32 v129, 0, v129
	v_max_f32_e32 v122, 0, v122
	v_max_f32_e32 v123, 0, v123
	v_max_f32_e32 v124, 0, v124
	v_max_f32_e32 v125, 0, v125
	v_pk_mul_f32 v[126:127], v[126:127], v[126:127]
	v_pk_mul_f32 v[128:129], v[128:129], v[128:129]
	v_pk_mul_f32 v[122:123], v[122:123], v[122:123]
	v_pk_mul_f32 v[124:125], v[124:125], v[124:125]
	v_cvt_pk_bf16_f32 v126, v126, v127
	v_cvt_pk_bf16_f32 v127, v128, v129
	v_cvt_pk_bf16_f32 v128, v122, v123
	v_cvt_pk_bf16_f32 v129, v124, v125
	v_pk_mul_f32 v[118:119], v[118:119], v[192:193] op_sel_hi:[1,0]
	v_pk_mul_f32 v[120:121], v[120:121], v[192:193] op_sel_hi:[1,0]
	v_pk_mul_f32 v[114:115], v[114:115], v[192:193] op_sel_hi:[1,0]
	v_pk_mul_f32 v[116:117], v[116:117], v[192:193] op_sel_hi:[1,0]
	v_max_f32_e32 v118, 0, v118
	v_max_f32_e32 v119, 0, v119
	v_max_f32_e32 v120, 0, v120
	v_max_f32_e32 v121, 0, v121
	v_max_f32_e32 v114, 0, v114
	v_max_f32_e32 v115, 0, v115
	v_max_f32_e32 v116, 0, v116
	v_max_f32_e32 v117, 0, v117
	v_pk_mul_f32 v[118:119], v[118:119], v[118:119]
	v_pk_mul_f32 v[120:121], v[120:121], v[120:121]
	v_pk_mul_f32 v[114:115], v[114:115], v[114:115]
	v_pk_mul_f32 v[116:117], v[116:117], v[116:117]
	v_cvt_pk_bf16_f32 v118, v118, v119
	v_cvt_pk_bf16_f32 v119, v120, v121
	v_cvt_pk_bf16_f32 v120, v114, v115
	v_cvt_pk_bf16_f32 v121, v116, v117
	s_mov_b64 vcc, s[98:99]
	v_cndmask_b32_dpp v122, v126, v118, vcc quad_perm:[1,0,3,2] row_mask:0xf bank_mask:0xf
	v_cndmask_b32_dpp v123, v127, v119, vcc quad_perm:[1,0,3,2] row_mask:0xf bank_mask:0xf
	v_cndmask_b32_dpp v124, v128, v120, vcc quad_perm:[1,0,3,2] row_mask:0xf bank_mask:0xf
	v_cndmask_b32_dpp v125, v129, v121, vcc quad_perm:[1,0,3,2] row_mask:0xf bank_mask:0xf
	s_mov_b64 vcc, s[92:93]
	v_cndmask_b32_dpp v126, v118, v126, vcc quad_perm:[1,0,3,2] row_mask:0xf bank_mask:0xf
	v_cndmask_b32_dpp v127, v119, v127, vcc quad_perm:[1,0,3,2] row_mask:0xf bank_mask:0xf
	v_cndmask_b32_dpp v128, v120, v128, vcc quad_perm:[1,0,3,2] row_mask:0xf bank_mask:0xf
	v_cndmask_b32_dpp v129, v121, v129, vcc quad_perm:[1,0,3,2] row_mask:0xf bank_mask:0xf
	global_store_dwordx4 v208, v[126:129], s[64:65] nt
	global_store_dwordx4 v209, v[122:125], s[64:65] nt
	s_waitcnt lgkmcnt(6)
; #define LAS __attribute__((address_space(3)))
; __device__ __forceinline__ unsigned cvt_pk_bf16(float lo, float hi) { unsigned r; asm volatile("v_cvt_pk_bf16_f32 %0, %1, %2" : "=v"(r) : "v"(lo), "v"(hi)); return r; }
;     __device__ __forceinline__ void operator()(const f32x4 (&acc)[2][2][4][2], const Unit& u, int wr, int wc, int fr, int fq) const {
;     ...
;         for (int ai = 0; ai < 2; ++ai)
; #pragma unroll
;             for (int m = 0; m < 4; ++m) {
;                 const float sc = __shfl(rl[ai], 16 * m + fr);
; #pragma unroll
;                 for (int bj = 0; bj < 2; ++bj) {
;                     f32x4 v0 = acc[ai][bj][m][0] * sc, v1 = acc[ai][bj][m][1] * sc;
;                     if (ACT == 1) {
; #pragma unroll
;                         for (int e = 0; e < 4; ++e) { float a = fmaxf(v0[e], 0.f), b = fmaxf(v1[e], 0.f); v0[e] = a * a; v1[e] = b * b; }
;                     }
;                     u32x4 w; w.x = cvt_pk_bf16(v0[0], v0[1]); w.y = cvt_pk_bf16(v0[2], v0[3]); w.z = cvt_pk_bf16(v1[0], v1[1]); w.w = cvt_pk_bf16(v1[2], v1[3]);
;                     *(LAS u32x4*)(sl + fr * 144 + bj * 64 + fq * 16) = w;
;                 }
;                 const int rowb = u.pm * BM + ai * HALF + wr * 64 + m * 16;
; #pragma unroll
;                 for (int i = 0; i < 2; ++i) { const int r = rr + 8 * i; const u32x4 q = *(const LAS u32x4*)(sl + r * 144 + cc * 16);
;                     __builtin_nontemporal_store(q, (u32x4*)(O + (size_t)(rowb + r) * ldc + colw + cc * 8)); }
	s_add_u32 s64, s62, 0x20000
	s_addc_u32 s65, s63, 0
	v_pk_mul_f32 v[110:111], v[110:111], v[194:195] op_sel_hi:[1,0]
	v_pk_mul_f32 v[112:113], v[112:113], v[194:195] op_sel_hi:[1,0]
	v_pk_mul_f32 v[106:107], v[106:107], v[194:195] op_sel_hi:[1,0]
	v_pk_mul_f32 v[108:109], v[108:109], v[194:195] op_sel_hi:[1,0]
	v_max_f32_e32 v110, 0, v110
	v_max_f32_e32 v111, 0, v111
	v_max_f32_e32 v112, 0, v112
	v_max_f32_e32 v113, 0, v113
	v_max_f32_e32 v106, 0, v106
	v_max_f32_e32 v107, 0, v107
	v_max_f32_e32 v108, 0, v108
	v_max_f32_e32 v109, 0, v109
	v_pk_mul_f32 v[110:111], v[110:111], v[110:111]
	v_pk_mul_f32 v[112:113], v[112:113], v[112:113]
	v_pk_mul_f32 v[106:107], v[106:107], v[106:107]
	v_pk_mul_f32 v[108:109], v[108:109], v[108:109]
	v_cvt_pk_bf16_f32 v110, v110, v111
	v_cvt_pk_bf16_f32 v111, v112, v113
	v_cvt_pk_bf16_f32 v112, v106, v107
	v_cvt_pk_bf16_f32 v113, v108, v109
	v_pk_mul_f32 v[102:103], v[102:103], v[194:195] op_sel_hi:[1,0]
	v_pk_mul_f32 v[104:105], v[104:105], v[194:195] op_sel_hi:[1,0]
	v_pk_mul_f32 v[98:99], v[98:99], v[194:195] op_sel_hi:[1,0]
	v_pk_mul_f32 v[100:101], v[100:101], v[194:195] op_sel_hi:[1,0]
	v_max_f32_e32 v102, 0, v102
	v_max_f32_e32 v103, 0, v103
	v_max_f32_e32 v104, 0, v104
	v_max_f32_e32 v105, 0, v105
	v_max_f32_e32 v98, 0, v98
	v_max_f32_e32 v99, 0, v99
	v_max_f32_e32 v100, 0, v100
	v_max_f32_e32 v101, 0, v101
	v_pk_mul_f32 v[102:103], v[102:103], v[102:103]
	v_pk_mul_f32 v[104:105], v[104:105], v[104:105]
	v_pk_mul_f32 v[98:99], v[98:99], v[98:99]
	v_pk_mul_f32 v[100:101], v[100:101], v[100:101]
	v_cvt_pk_bf16_f32 v102, v102, v103
	v_cvt_pk_bf16_f32 v103, v104, v105
	v_cvt_pk_bf16_f32 v104, v98, v99
	v_cvt_pk_bf16_f32 v105, v100, v101
	s_mov_b64 vcc, s[98:99]
	v_cndmask_b32_dpp v106, v110, v102, vcc quad_perm:[1,0,3,2] row_mask:0xf bank_mask:0xf
	v_cndmask_b32_dpp v107, v111, v103, vcc quad_perm:[1,0,3,2] row_mask:0xf bank_mask:0xf
	v_cndmask_b32_dpp v108, v112, v104, vcc quad_perm:[1,0,3,2] row_mask:0xf bank_mask:0xf
	v_cndmask_b32_dpp v109, v113, v105, vcc quad_perm:[1,0,3,2] row_mask:0xf bank_mask:0xf
	s_mov_b64 vcc, s[92:93]
	v_cndmask_b32_dpp v110, v102, v110, vcc quad_perm:[1,0,3,2] row_mask:0xf bank_mask:0xf
	v_cndmask_b32_dpp v111, v103, v111, vcc quad_perm:[1,0,3,2] row_mask:0xf bank_mask:0xf
	v_cndmask_b32_dpp v112, v104, v112, vcc quad_perm:[1,0,3,2] row_mask:0xf bank_mask:0xf
	v_cndmask_b32_dpp v113, v105, v113, vcc quad_perm:[1,0,3,2] row_mask:0xf bank_mask:0xf
	global_store_dwordx4 v208, v[110:113], s[64:65] nt
	global_store_dwordx4 v209, v[106:109], s[64:65] nt
	s_waitcnt lgkmcnt(5)
	s_add_u32 s64, s62, 0x40000
	s_addc_u32 s65, s63, 0
	v_pk_mul_f32 v[94:95], v[94:95], v[196:197] op_sel_hi:[1,0]
	v_pk_mul_f32 v[96:97], v[96:97], v[196:197] op_sel_hi:[1,0]
	v_pk_mul_f32 v[90:91], v[90:91], v[196:197] op_sel_hi:[1,0]
	v_pk_mul_f32 v[92:93], v[92:93], v[196:197] op_sel_hi:[1,0]
	v_max_f32_e32 v94, 0, v94
	v_max_f32_e32 v95, 0, v95
	v_max_f32_e32 v96, 0, v96
	v_max_f32_e32 v97, 0, v97
	v_max_f32_e32 v90, 0, v90
	v_max_f32_e32 v91, 0, v91
	v_max_f32_e32 v92, 0, v92
	v_max_f32_e32 v93, 0, v93
	v_pk_mul_f32 v[94:95], v[94:95], v[94:95]
	v_pk_mul_f32 v[96:97], v[96:97], v[96:97]
	v_pk_mul_f32 v[90:91], v[90:91], v[90:91]
	v_pk_mul_f32 v[92:93], v[92:93], v[92:93]
	v_cvt_pk_bf16_f32 v94, v94, v95
	v_cvt_pk_bf16_f32 v95, v96, v97
	v_cvt_pk_bf16_f32 v96, v90, v91
	v_cvt_pk_bf16_f32 v97, v92, v93
	v_pk_mul_f32 v[86:87], v[86:87], v[196:197] op_sel_hi:[1,0]
	v_pk_mul_f32 v[88:89], v[88:89], v[196:197] op_sel_hi:[1,0]
	v_pk_mul_f32 v[82:83], v[82:83], v[196:197] op_sel_hi:[1,0]
	v_pk_mul_f32 v[84:85], v[84:85], v[196:197] op_sel_hi:[1,0]
	v_max_f32_e32 v86, 0, v86
	v_max_f32_e32 v87, 0, v87
	v_max_f32_e32 v88, 0, v88
	v_max_f32_e32 v89, 0, v89
	v_max_f32_e32 v82, 0, v82
	v_max_f32_e32 v83, 0, v83
	v_max_f32_e32 v84, 0, v84
	v_max_f32_e32 v85, 0, v85
	v_pk_mul_f32 v[86:87], v[86:87], v[86:87]
	v_pk_mul_f32 v[88:89], v[88:89], v[88:89]
	v_pk_mul_f32 v[82:83], v[82:83], v[82:83]
	v_pk_mul_f32 v[84:85], v[84:85], v[84:85]
	v_cvt_pk_bf16_f32 v86, v86, v87
	v_cvt_pk_bf16_f32 v87, v88, v89
	v_cvt_pk_bf16_f32 v88, v82, v83
	v_cvt_pk_bf16_f32 v89, v84, v85
	s_mov_b64 vcc, s[98:99]
	v_cndmask_b32_dpp v90, v94, v86, vcc quad_perm:[1,0,3,2] row_mask:0xf bank_mask:0xf
	v_cndmask_b32_dpp v91, v95, v87, vcc quad_perm:[1,0,3,2] row_mask:0xf bank_mask:0xf
	v_cndmask_b32_dpp v92, v96, v88, vcc quad_perm:[1,0,3,2] row_mask:0xf bank_mask:0xf
	v_cndmask_b32_dpp v93, v97, v89, vcc quad_perm:[1,0,3,2] row_mask:0xf bank_mask:0xf
	s_mov_b64 vcc, s[92:93]
	v_cndmask_b32_dpp v94, v86, v94, vcc quad_perm:[1,0,3,2] row_mask:0xf bank_mask:0xf
	v_cndmask_b32_dpp v95, v87, v95, vcc quad_perm:[1,0,3,2] row_mask:0xf bank_mask:0xf
	v_cndmask_b32_dpp v96, v88, v96, vcc quad_perm:[1,0,3,2] row_mask:0xf bank_mask:0xf
	v_cndmask_b32_dpp v97, v89, v97, vcc quad_perm:[1,0,3,2] row_mask:0xf bank_mask:0xf
	global_store_dwordx4 v208, v[94:97], s[64:65] nt
	global_store_dwordx4 v209, v[90:93], s[64:65] nt
	s_waitcnt lgkmcnt(4)
; #define LAS __attribute__((address_space(3)))
; __device__ __forceinline__ unsigned cvt_pk_bf16(float lo, float hi) { unsigned r; asm volatile("v_cvt_pk_bf16_f32 %0, %1, %2" : "=v"(r) : "v"(lo), "v"(hi)); return r; }
;     __device__ __forceinline__ void operator()(const f32x4 (&acc)[2][2][4][2], const Unit& u, int wr, int wc, int fr, int fq) const {
;     ...
;         for (int ai = 0; ai < 2; ++ai)
; #pragma unroll
;             for (int m = 0; m < 4; ++m) {
;                 const float sc = __shfl(rl[ai], 16 * m + fr);
; #pragma unroll
;                 for (int bj = 0; bj < 2; ++bj) {
;                     f32x4 v0 = acc[ai][bj][m][0] * sc, v1 = acc[ai][bj][m][1] * sc;
;                     if (ACT == 1) {
; #pragma unroll
;                         for (int e = 0; e < 4; ++e) { float a = fmaxf(v0[e], 0.f), b = fmaxf(v1[e], 0.f); v0[e] = a * a; v1[e] = b * b; }
;                     }
;                     u32x4 w; w.x = cvt_pk_bf16(v0[0], v0[1]); w.y = cvt_pk_bf16(v0[2], v0[3]); w.z = cvt_pk_bf16(v1[0], v1[1]); w.w = cvt_pk_bf16(v1[2], v1[3]);
;                     *(LAS u32x4*)(sl + fr * 144 + bj * 64 + fq * 16) = w;
;                 }
;                 const int rowb = u.pm * BM + ai * HALF + wr * 64 + m * 16;
; #pragma unroll
;                 for (int i = 0; i < 2; ++i) { const int r = rr + 8 * i; const u32x4 q = *(const LAS u32x4*)(sl + r * 144 + cc * 16);
;                     __builtin_nontemporal_store(q, (u32x4*)(O + (size_t)(rowb + r) * ldc + colw + cc * 8)); }
	s_add_u32 s64, s62, 0x60000
	s_addc_u32 s65, s63, 0
	v_pk_mul_f32 v[78:79], v[78:79], v[198:199] op_sel_hi:[1,0]
	v_pk_mul_f32 v[80:81], v[80:81], v[198:199] op_sel_hi:[1,0]
	v_pk_mul_f32 v[74:75], v[74:75], v[198:199] op_sel_hi:[1,0]
	v_pk_mul_f32 v[76:77], v[76:77], v[198:199] op_sel_hi:[1,0]
	v_max_f32_e32 v78, 0, v78
	v_max_f32_e32 v79, 0, v79
	v_max_f32_e32 v80, 0, v80
	v_max_f32_e32 v81, 0, v81
	v_max_f32_e32 v74, 0, v74
	v_max_f32_e32 v75, 0, v75
	v_max_f32_e32 v76, 0, v76
	v_max_f32_e32 v77, 0, v77
	v_pk_mul_f32 v[78:79], v[78:79], v[78:79]
	v_pk_mul_f32 v[80:81], v[80:81], v[80:81]
	v_pk_mul_f32 v[74:75], v[74:75], v[74:75]
	v_pk_mul_f32 v[76:77], v[76:77], v[76:77]
	v_cvt_pk_bf16_f32 v78, v78, v79
	v_cvt_pk_bf16_f32 v79, v80, v81
	v_cvt_pk_bf16_f32 v80, v74, v75
	v_cvt_pk_bf16_f32 v81, v76, v77
	v_pk_mul_f32 v[70:71], v[70:71], v[198:199] op_sel_hi:[1,0]
	v_pk_mul_f32 v[72:73], v[72:73], v[198:199] op_sel_hi:[1,0]
	v_pk_mul_f32 v[66:67], v[66:67], v[198:199] op_sel_hi:[1,0]
	v_pk_mul_f32 v[68:69], v[68:69], v[198:199] op_sel_hi:[1,0]
	v_max_f32_e32 v70, 0, v70
	v_max_f32_e32 v71, 0, v71
	v_max_f32_e32 v72, 0, v72
	v_max_f32_e32 v73, 0, v73
	v_max_f32_e32 v66, 0, v66
	v_max_f32_e32 v67, 0, v67
	v_max_f32_e32 v68, 0, v68
	v_max_f32_e32 v69, 0, v69
	v_pk_mul_f32 v[70:71], v[70:71], v[70:71]
	v_pk_mul_f32 v[72:73], v[72:73], v[72:73]
	v_pk_mul_f32 v[66:67], v[66:67], v[66:67]
	v_pk_mul_f32 v[68:69], v[68:69], v[68:69]
	v_cvt_pk_bf16_f32 v70, v70, v71
	v_cvt_pk_bf16_f32 v71, v72, v73
	v_cvt_pk_bf16_f32 v72, v66, v67
	v_cvt_pk_bf16_f32 v73, v68, v69
	s_mov_b64 vcc, s[98:99]
	v_cndmask_b32_dpp v74, v78, v70, vcc quad_perm:[1,0,3,2] row_mask:0xf bank_mask:0xf
	v_cndmask_b32_dpp v75, v79, v71, vcc quad_perm:[1,0,3,2] row_mask:0xf bank_mask:0xf
	v_cndmask_b32_dpp v76, v80, v72, vcc quad_perm:[1,0,3,2] row_mask:0xf bank_mask:0xf
	v_cndmask_b32_dpp v77, v81, v73, vcc quad_perm:[1,0,3,2] row_mask:0xf bank_mask:0xf
	s_mov_b64 vcc, s[92:93]
	v_cndmask_b32_dpp v78, v70, v78, vcc quad_perm:[1,0,3,2] row_mask:0xf bank_mask:0xf
	v_cndmask_b32_dpp v79, v71, v79, vcc quad_perm:[1,0,3,2] row_mask:0xf bank_mask:0xf
	v_cndmask_b32_dpp v80, v72, v80, vcc quad_perm:[1,0,3,2] row_mask:0xf bank_mask:0xf
	v_cndmask_b32_dpp v81, v73, v81, vcc quad_perm:[1,0,3,2] row_mask:0xf bank_mask:0xf
	global_store_dwordx4 v208, v[78:81], s[64:65] nt
	global_store_dwordx4 v209, v[74:77], s[64:65] nt
	s_waitcnt lgkmcnt(3)
	s_add_u32 s64, s62, 0x100000
	s_addc_u32 s65, s63, 0
	v_pk_mul_f32 v[62:63], v[62:63], v[200:201] op_sel_hi:[1,0]
	v_pk_mul_f32 v[64:65], v[64:65], v[200:201] op_sel_hi:[1,0]
	v_pk_mul_f32 v[58:59], v[58:59], v[200:201] op_sel_hi:[1,0]
	v_pk_mul_f32 v[60:61], v[60:61], v[200:201] op_sel_hi:[1,0]
	v_max_f32_e32 v62, 0, v62
	v_max_f32_e32 v63, 0, v63
	v_max_f32_e32 v64, 0, v64
	v_max_f32_e32 v65, 0, v65
	v_max_f32_e32 v58, 0, v58
	v_max_f32_e32 v59, 0, v59
	v_max_f32_e32 v60, 0, v60
	v_max_f32_e32 v61, 0, v61
	v_pk_mul_f32 v[62:63], v[62:63], v[62:63]
	v_pk_mul_f32 v[64:65], v[64:65], v[64:65]
	v_pk_mul_f32 v[58:59], v[58:59], v[58:59]
	v_pk_mul_f32 v[60:61], v[60:61], v[60:61]
	v_cvt_pk_bf16_f32 v62, v62, v63
	v_cvt_pk_bf16_f32 v63, v64, v65
	v_cvt_pk_bf16_f32 v64, v58, v59
	v_cvt_pk_bf16_f32 v65, v60, v61
	v_pk_mul_f32 v[54:55], v[54:55], v[200:201] op_sel_hi:[1,0]
	v_pk_mul_f32 v[56:57], v[56:57], v[200:201] op_sel_hi:[1,0]
	v_pk_mul_f32 v[50:51], v[50:51], v[200:201] op_sel_hi:[1,0]
	v_pk_mul_f32 v[52:53], v[52:53], v[200:201] op_sel_hi:[1,0]
	v_max_f32_e32 v54, 0, v54
	v_max_f32_e32 v55, 0, v55
	v_max_f32_e32 v56, 0, v56
	v_max_f32_e32 v57, 0, v57
	v_max_f32_e32 v50, 0, v50
	v_max_f32_e32 v51, 0, v51
	v_max_f32_e32 v52, 0, v52
	v_max_f32_e32 v53, 0, v53
	v_pk_mul_f32 v[54:55], v[54:55], v[54:55]
	v_pk_mul_f32 v[56:57], v[56:57], v[56:57]
	v_pk_mul_f32 v[50:51], v[50:51], v[50:51]
	v_pk_mul_f32 v[52:53], v[52:53], v[52:53]
	v_cvt_pk_bf16_f32 v54, v54, v55
	v_cvt_pk_bf16_f32 v55, v56, v57
	v_cvt_pk_bf16_f32 v56, v50, v51
	v_cvt_pk_bf16_f32 v57, v52, v53
	s_mov_b64 vcc, s[98:99]
	v_cndmask_b32_dpp v58, v62, v54, vcc quad_perm:[1,0,3,2] row_mask:0xf bank_mask:0xf
	v_cndmask_b32_dpp v59, v63, v55, vcc quad_perm:[1,0,3,2] row_mask:0xf bank_mask:0xf
	v_cndmask_b32_dpp v60, v64, v56, vcc quad_perm:[1,0,3,2] row_mask:0xf bank_mask:0xf
	v_cndmask_b32_dpp v61, v65, v57, vcc quad_perm:[1,0,3,2] row_mask:0xf bank_mask:0xf
	s_mov_b64 vcc, s[92:93]
	v_cndmask_b32_dpp v62, v54, v62, vcc quad_perm:[1,0,3,2] row_mask:0xf bank_mask:0xf
	v_cndmask_b32_dpp v63, v55, v63, vcc quad_perm:[1,0,3,2] row_mask:0xf bank_mask:0xf
	v_cndmask_b32_dpp v64, v56, v64, vcc quad_perm:[1,0,3,2] row_mask:0xf bank_mask:0xf
	v_cndmask_b32_dpp v65, v57, v65, vcc quad_perm:[1,0,3,2] row_mask:0xf bank_mask:0xf
	global_store_dwordx4 v208, v[62:65], s[64:65] nt
	global_store_dwordx4 v209, v[58:61], s[64:65] nt
	s_waitcnt lgkmcnt(2)
; #define LAS __attribute__((address_space(3)))
; __device__ __forceinline__ unsigned cvt_pk_bf16(float lo, float hi) { unsigned r; asm volatile("v_cvt_pk_bf16_f32 %0, %1, %2" : "=v"(r) : "v"(lo), "v"(hi)); return r; }
;     __device__ __forceinline__ void operator()(const f32x4 (&acc)[2][2][4][2], const Unit& u, int wr, int wc, int fr, int fq) const {
;     ...
;         for (int ai = 0; ai < 2; ++ai)
; #pragma unroll
;             for (int m = 0; m < 4; ++m) {
;                 const float sc = __shfl(rl[ai], 16 * m + fr);
; #pragma unroll
;                 for (int bj = 0; bj < 2; ++bj) {
;                     f32x4 v0 = acc[ai][bj][m][0] * sc, v1 = acc[ai][bj][m][1] * sc;
;                     if (ACT == 1) {
; #pragma unroll
;                         for (int e = 0; e < 4; ++e) { float a = fmaxf(v0[e], 0.f), b = fmaxf(v1[e], 0.f); v0[e] = a * a; v1[e] = b * b; }
;                     }
;                     u32x4 w; w.x = cvt_pk_bf16(v0[0], v0[1]); w.y = cvt_pk_bf16(v0[2], v0[3]); w.z = cvt_pk_bf16(v1[0], v1[1]); w.w = cvt_pk_bf16(v1[2], v1[3]);
;                     *(LAS u32x4*)(sl + fr * 144 + bj * 64 + fq * 16) = w;
;                 }
;                 const int rowb = u.pm * BM + ai * HALF + wr * 64 + m * 16;
; #pragma unroll
;                 for (int i = 0; i < 2; ++i) { const int r = rr + 8 * i; const u32x4 q = *(const LAS u32x4*)(sl + r * 144 + cc * 16);
;                     __builtin_nontemporal_store(q, (u32x4*)(O + (size_t)(rowb + r) * ldc + colw + cc * 8)); }
	s_add_u32 s64, s62, 0x120000
	s_addc_u32 s65, s63, 0
	v_pk_mul_f32 v[46:47], v[46:47], v[202:203] op_sel_hi:[1,0]
	v_pk_mul_f32 v[48:49], v[48:49], v[202:203] op_sel_hi:[1,0]
	v_pk_mul_f32 v[42:43], v[42:43], v[202:203] op_sel_hi:[1,0]
	v_pk_mul_f32 v[44:45], v[44:45], v[202:203] op_sel_hi:[1,0]
	v_max_f32_e32 v46, 0, v46
	v_max_f32_e32 v47, 0, v47
	v_max_f32_e32 v48, 0, v48
	v_max_f32_e32 v49, 0, v49
	v_max_f32_e32 v42, 0, v42
	v_max_f32_e32 v43, 0, v43
	v_max_f32_e32 v44, 0, v44
	v_max_f32_e32 v45, 0, v45
	v_pk_mul_f32 v[46:47], v[46:47], v[46:47]
	v_pk_mul_f32 v[48:49], v[48:49], v[48:49]
	v_pk_mul_f32 v[42:43], v[42:43], v[42:43]
	v_pk_mul_f32 v[44:45], v[44:45], v[44:45]
	v_cvt_pk_bf16_f32 v46, v46, v47
	v_cvt_pk_bf16_f32 v47, v48, v49
	v_cvt_pk_bf16_f32 v48, v42, v43
	v_cvt_pk_bf16_f32 v49, v44, v45
	v_pk_mul_f32 v[38:39], v[38:39], v[202:203] op_sel_hi:[1,0]
	v_pk_mul_f32 v[40:41], v[40:41], v[202:203] op_sel_hi:[1,0]
	v_pk_mul_f32 v[34:35], v[34:35], v[202:203] op_sel_hi:[1,0]
	v_pk_mul_f32 v[36:37], v[36:37], v[202:203] op_sel_hi:[1,0]
	v_max_f32_e32 v38, 0, v38
	v_max_f32_e32 v39, 0, v39
	v_max_f32_e32 v40, 0, v40
	v_max_f32_e32 v41, 0, v41
	v_max_f32_e32 v34, 0, v34
	v_max_f32_e32 v35, 0, v35
	v_max_f32_e32 v36, 0, v36
	v_max_f32_e32 v37, 0, v37
	v_pk_mul_f32 v[38:39], v[38:39], v[38:39]
	v_pk_mul_f32 v[40:41], v[40:41], v[40:41]
	v_pk_mul_f32 v[34:35], v[34:35], v[34:35]
	v_pk_mul_f32 v[36:37], v[36:37], v[36:37]
	v_cvt_pk_bf16_f32 v38, v38, v39
	v_cvt_pk_bf16_f32 v39, v40, v41
	v_cvt_pk_bf16_f32 v40, v34, v35
	v_cvt_pk_bf16_f32 v41, v36, v37
	s_mov_b64 vcc, s[98:99]
	v_cndmask_b32_dpp v42, v46, v38, vcc quad_perm:[1,0,3,2] row_mask:0xf bank_mask:0xf
	v_cndmask_b32_dpp v43, v47, v39, vcc quad_perm:[1,0,3,2] row_mask:0xf bank_mask:0xf
	v_cndmask_b32_dpp v44, v48, v40, vcc quad_perm:[1,0,3,2] row_mask:0xf bank_mask:0xf
	v_cndmask_b32_dpp v45, v49, v41, vcc quad_perm:[1,0,3,2] row_mask:0xf bank_mask:0xf
	s_mov_b64 vcc, s[92:93]
	v_cndmask_b32_dpp v46, v38, v46, vcc quad_perm:[1,0,3,2] row_mask:0xf bank_mask:0xf
	v_cndmask_b32_dpp v47, v39, v47, vcc quad_perm:[1,0,3,2] row_mask:0xf bank_mask:0xf
	v_cndmask_b32_dpp v48, v40, v48, vcc quad_perm:[1,0,3,2] row_mask:0xf bank_mask:0xf
	v_cndmask_b32_dpp v49, v41, v49, vcc quad_perm:[1,0,3,2] row_mask:0xf bank_mask:0xf
	global_store_dwordx4 v208, v[46:49], s[64:65] nt
	global_store_dwordx4 v209, v[42:45], s[64:65] nt
	s_waitcnt lgkmcnt(1)
; #define LAS __attribute__((address_space(3)))
; __device__ __forceinline__ unsigned cvt_pk_bf16(float lo, float hi) { unsigned r; asm volatile("v_cvt_pk_bf16_f32 %0, %1, %2" : "=v"(r) : "v"(lo), "v"(hi)); return r; }
;     __device__ __forceinline__ void operator()(const f32x4 (&acc)[2][2][4][2], const Unit& u, int wr, int wc, int fr, int fq) const {
;     ...
;         for (int ai = 0; ai < 2; ++ai)
; #pragma unroll
;             for (int m = 0; m < 4; ++m) {
;                 const float sc = __shfl(rl[ai], 16 * m + fr);
; #pragma unroll
;                 for (int bj = 0; bj < 2; ++bj) {
;                     f32x4 v0 = acc[ai][bj][m][0] * sc, v1 = acc[ai][bj][m][1] * sc;
;                     if (ACT == 1) {
; #pragma unroll
;                         for (int e = 0; e < 4; ++e) { float a = fmaxf(v0[e], 0.f), b = fmaxf(v1[e], 0.f); v0[e] = a * a; v1[e] = b * b; }
;                     }
;                     u32x4 w; w.x = cvt_pk_bf16(v0[0], v0[1]); w.y = cvt_pk_bf16(v0[2], v0[3]); w.z = cvt_pk_bf16(v1[0], v1[1]); w.w = cvt_pk_bf16(v1[2], v1[3]);
;                     *(LAS u32x4*)(sl + fr * 144 + bj * 64 + fq * 16) = w;
;                 }
;                 const int rowb = u.pm * BM + ai * HALF + wr * 64 + m * 16;
; #pragma unroll
;                 for (int i = 0; i < 2; ++i) { const int r = rr + 8 * i; const u32x4 q = *(const LAS u32x4*)(sl + r * 144 + cc * 16);
;                     __builtin_nontemporal_store(q, (u32x4*)(O + (size_t)(rowb + r) * ldc + colw + cc * 8)); }
	s_add_u32 s64, s62, 0x140000
	s_addc_u32 s65, s63, 0
	v_pk_mul_f32 v[30:31], v[30:31], v[204:205] op_sel_hi:[1,0]
	v_pk_mul_f32 v[32:33], v[32:33], v[204:205] op_sel_hi:[1,0]
	v_pk_mul_f32 v[26:27], v[26:27], v[204:205] op_sel_hi:[1,0]
	v_pk_mul_f32 v[28:29], v[28:29], v[204:205] op_sel_hi:[1,0]
	v_max_f32_e32 v30, 0, v30
	v_max_f32_e32 v31, 0, v31
	v_max_f32_e32 v32, 0, v32
	v_max_f32_e32 v33, 0, v33
	v_max_f32_e32 v26, 0, v26
	v_max_f32_e32 v27, 0, v27
	v_max_f32_e32 v28, 0, v28
	v_max_f32_e32 v29, 0, v29
	v_pk_mul_f32 v[30:31], v[30:31], v[30:31]
	v_pk_mul_f32 v[32:33], v[32:33], v[32:33]
	v_pk_mul_f32 v[26:27], v[26:27], v[26:27]
	v_pk_mul_f32 v[28:29], v[28:29], v[28:29]
	v_cvt_pk_bf16_f32 v30, v30, v31
	v_cvt_pk_bf16_f32 v31, v32, v33
	v_cvt_pk_bf16_f32 v32, v26, v27
	v_cvt_pk_bf16_f32 v33, v28, v29
	v_pk_mul_f32 v[22:23], v[22:23], v[204:205] op_sel_hi:[1,0]
	v_pk_mul_f32 v[24:25], v[24:25], v[204:205] op_sel_hi:[1,0]
	v_pk_mul_f32 v[18:19], v[18:19], v[204:205] op_sel_hi:[1,0]
	v_pk_mul_f32 v[20:21], v[20:21], v[204:205] op_sel_hi:[1,0]
	v_max_f32_e32 v22, 0, v22
	v_max_f32_e32 v23, 0, v23
	v_max_f32_e32 v24, 0, v24
	v_max_f32_e32 v25, 0, v25
	v_max_f32_e32 v18, 0, v18
	v_max_f32_e32 v19, 0, v19
	v_max_f32_e32 v20, 0, v20
	v_max_f32_e32 v21, 0, v21
	v_pk_mul_f32 v[22:23], v[22:23], v[22:23]
	v_pk_mul_f32 v[24:25], v[24:25], v[24:25]
	v_pk_mul_f32 v[18:19], v[18:19], v[18:19]
	v_pk_mul_f32 v[20:21], v[20:21], v[20:21]
	v_cvt_pk_bf16_f32 v22, v22, v23
	v_cvt_pk_bf16_f32 v23, v24, v25
	v_cvt_pk_bf16_f32 v24, v18, v19
	v_cvt_pk_bf16_f32 v25, v20, v21
	s_mov_b64 vcc, s[98:99]
	v_cndmask_b32_dpp v26, v30, v22, vcc quad_perm:[1,0,3,2] row_mask:0xf bank_mask:0xf
	v_cndmask_b32_dpp v27, v31, v23, vcc quad_perm:[1,0,3,2] row_mask:0xf bank_mask:0xf
	v_cndmask_b32_dpp v28, v32, v24, vcc quad_perm:[1,0,3,2] row_mask:0xf bank_mask:0xf
	v_cndmask_b32_dpp v29, v33, v25, vcc quad_perm:[1,0,3,2] row_mask:0xf bank_mask:0xf
	s_mov_b64 vcc, s[92:93]
	v_cndmask_b32_dpp v30, v22, v30, vcc quad_perm:[1,0,3,2] row_mask:0xf bank_mask:0xf
	v_cndmask_b32_dpp v31, v23, v31, vcc quad_perm:[1,0,3,2] row_mask:0xf bank_mask:0xf
	v_cndmask_b32_dpp v32, v24, v32, vcc quad_perm:[1,0,3,2] row_mask:0xf bank_mask:0xf
	v_cndmask_b32_dpp v33, v25, v33, vcc quad_perm:[1,0,3,2] row_mask:0xf bank_mask:0xf
	global_store_dwordx4 v208, v[30:33], s[64:65] nt
	global_store_dwordx4 v209, v[26:29], s[64:65] nt
	s_waitcnt lgkmcnt(0)
	s_add_u32 s64, s62, 0x160000
	s_addc_u32 s65, s63, 0
	v_pk_mul_f32 v[14:15], v[14:15], v[206:207] op_sel_hi:[1,0]
	v_pk_mul_f32 v[16:17], v[16:17], v[206:207] op_sel_hi:[1,0]
	v_pk_mul_f32 v[10:11], v[10:11], v[206:207] op_sel_hi:[1,0]
	v_pk_mul_f32 v[12:13], v[12:13], v[206:207] op_sel_hi:[1,0]
	v_max_f32_e32 v14, 0, v14
	v_max_f32_e32 v15, 0, v15
	v_max_f32_e32 v16, 0, v16
	v_max_f32_e32 v17, 0, v17
	v_max_f32_e32 v10, 0, v10
	v_max_f32_e32 v11, 0, v11
	v_max_f32_e32 v12, 0, v12
	v_max_f32_e32 v13, 0, v13
	v_pk_mul_f32 v[14:15], v[14:15], v[14:15]
	v_pk_mul_f32 v[16:17], v[16:17], v[16:17]
	v_pk_mul_f32 v[10:11], v[10:11], v[10:11]
	v_pk_mul_f32 v[12:13], v[12:13], v[12:13]
	v_cvt_pk_bf16_f32 v14, v14, v15
	v_cvt_pk_bf16_f32 v15, v16, v17
	v_cvt_pk_bf16_f32 v16, v10, v11
	v_cvt_pk_bf16_f32 v17, v12, v13
	v_pk_mul_f32 v[6:7], v[6:7], v[206:207] op_sel_hi:[1,0]
	v_pk_mul_f32 v[8:9], v[8:9], v[206:207] op_sel_hi:[1,0]
	v_pk_mul_f32 v[2:3], v[2:3], v[206:207] op_sel_hi:[1,0]
	v_pk_mul_f32 v[4:5], v[4:5], v[206:207] op_sel_hi:[1,0]
	v_max_f32_e32 v6, 0, v6
	v_max_f32_e32 v7, 0, v7
	v_max_f32_e32 v8, 0, v8
	v_max_f32_e32 v9, 0, v9
	v_max_f32_e32 v2, 0, v2
	v_max_f32_e32 v3, 0, v3
	v_max_f32_e32 v4, 0, v4
	v_max_f32_e32 v5, 0, v5
	v_pk_mul_f32 v[6:7], v[6:7], v[6:7]
	v_pk_mul_f32 v[8:9], v[8:9], v[8:9]
	v_pk_mul_f32 v[2:3], v[2:3], v[2:3]
	v_pk_mul_f32 v[4:5], v[4:5], v[4:5]
	v_cvt_pk_bf16_f32 v6, v6, v7
	v_cvt_pk_bf16_f32 v7, v8, v9
	v_cvt_pk_bf16_f32 v8, v2, v3
	v_cvt_pk_bf16_f32 v9, v4, v5
	s_mov_b64 vcc, s[98:99]
	v_cndmask_b32_dpp v10, v14, v6, vcc quad_perm:[1,0,3,2] row_mask:0xf bank_mask:0xf
	v_cndmask_b32_dpp v11, v15, v7, vcc quad_perm:[1,0,3,2] row_mask:0xf bank_mask:0xf
	v_cndmask_b32_dpp v12, v16, v8, vcc quad_perm:[1,0,3,2] row_mask:0xf bank_mask:0xf
	v_cndmask_b32_dpp v13, v17, v9, vcc quad_perm:[1,0,3,2] row_mask:0xf bank_mask:0xf
	s_mov_b64 vcc, s[92:93]
	v_cndmask_b32_dpp v14, v6, v14, vcc quad_perm:[1,0,3,2] row_mask:0xf bank_mask:0xf
	v_cndmask_b32_dpp v15, v7, v15, vcc quad_perm:[1,0,3,2] row_mask:0xf bank_mask:0xf
	v_cndmask_b32_dpp v16, v8, v16, vcc quad_perm:[1,0,3,2] row_mask:0xf bank_mask:0xf
	v_cndmask_b32_dpp v17, v9, v17, vcc quad_perm:[1,0,3,2] row_mask:0xf bank_mask:0xf
	global_store_dwordx4 v208, v[14:17], s[64:65] nt
	global_store_dwordx4 v209, v[10:13], s[64:65] nt
	s_andn2_b64 vcc, exec, s[38:39]
	s_mov_b64 s[26:27], -1
	s_cbranch_vccnz .LBB0_506
